# attention: 512 sample queries spread over waves 0-1 of all 256 workgroups (XCD = sample sequence) instead of a ninth round on 64 workgroups; plus c3
# baseline (speedup 1.0000x reference)
; __device__ __forceinline__ void attn_phase(const Args& a, unsigned char* lds, int lane, int wave) {
;     ...
;             for (int i = 0; i < 8; ++i) { const int idx = (int)(i < 4 ? ida[i & 3] : idb[i & 3]); const unsigned char* kp;
;                 if (!sample) kp = KV8 + (size_t)idx * 2048;
;                 else if (idx < 1024) kp = CKV8 + (size_t)(bb * 1024 + idx) * 2048;
;                 else kp = KV8 + (size_t)(TP + bb * 64 + idx - 1024) * 2048;
;                 kk[i] = *(const u32x4*)(kp + lane * 16); vv[i] = *(const u32x4*)(kp + 1024 + lane * 16); }
;             float s[8];
; #pragma unroll
;             for (int i = 0; i < 8; ++i) { float kf[16]; unpack16_fp8(kk[i], kf); float d0 = 0.f, d1 = 0.f;
; #pragma unroll
;                 for (int x = 0; x < 16; x += 2) { d0 += q[x] * kf[x]; d1 += q[x + 1] * kf[x + 1]; }
;                 float d = d0 + d1;
;                 d += __shfl_xor(d, 1); d += __shfl_xor(d, 2); d += __shfl_xor(d, 4); s[i] = d; }
.Lat_blk:
	s_waitcnt vmcnt(30)
	v_cvt_pk_f32_fp8_e32 v[204:205], v132
	v_cvt_pk_f32_fp8_e32 v[206:207], v136
	v_pk_mul_f32 v[220:221], v[204:205], v[78:79]
	v_pk_mul_f32 v[222:223], v[206:207], v[78:79]
	v_cvt_pk_f32_fp8_sdwa v[208:209], v132 src0_sel:WORD_1
	v_cvt_pk_f32_fp8_sdwa v[210:211], v136 src0_sel:WORD_1
	v_pk_fma_f32 v[220:221], v[208:209], v[80:81], v[220:221]
	v_pk_fma_f32 v[222:223], v[210:211], v[80:81], v[222:223]
	v_cvt_pk_f32_fp8_e32 v[212:213], v133
	v_cvt_pk_f32_fp8_e32 v[214:215], v137
	v_pk_fma_f32 v[220:221], v[212:213], v[82:83], v[220:221]
	v_pk_fma_f32 v[222:223], v[214:215], v[82:83], v[222:223]
	v_cvt_pk_f32_fp8_sdwa v[216:217], v133 src0_sel:WORD_1
	v_cvt_pk_f32_fp8_sdwa v[218:219], v137 src0_sel:WORD_1
	v_pk_fma_f32 v[220:221], v[216:217], v[84:85], v[220:221]
	v_pk_fma_f32 v[222:223], v[218:219], v[84:85], v[222:223]
	v_cvt_pk_f32_fp8_e32 v[204:205], v134
	v_cvt_pk_f32_fp8_e32 v[206:207], v138
	v_pk_fma_f32 v[220:221], v[204:205], v[86:87], v[220:221]
	v_pk_fma_f32 v[222:223], v[206:207], v[86:87], v[222:223]
	v_cvt_pk_f32_fp8_sdwa v[208:209], v134 src0_sel:WORD_1
	v_cvt_pk_f32_fp8_sdwa v[210:211], v138 src0_sel:WORD_1
	v_pk_fma_f32 v[220:221], v[208:209], v[88:89], v[220:221]
	v_pk_fma_f32 v[222:223], v[210:211], v[88:89], v[222:223]
	v_cvt_pk_f32_fp8_e32 v[212:213], v135
	v_cvt_pk_f32_fp8_e32 v[214:215], v139
	v_pk_fma_f32 v[220:221], v[212:213], v[90:91], v[220:221]
	v_pk_fma_f32 v[222:223], v[214:215], v[90:91], v[222:223]
	v_cvt_pk_f32_fp8_sdwa v[216:217], v135 src0_sel:WORD_1
	v_cvt_pk_f32_fp8_sdwa v[218:219], v139 src0_sel:WORD_1
	v_pk_fma_f32 v[220:221], v[216:217], v[92:93], v[220:221]
	v_pk_fma_f32 v[222:223], v[218:219], v[92:93], v[222:223]
	s_waitcnt vmcnt(28)
	v_cvt_pk_f32_fp8_e32 v[204:205], v140
	v_cvt_pk_f32_fp8_e32 v[206:207], v144
	v_pk_mul_f32 v[224:225], v[204:205], v[78:79]
	v_pk_mul_f32 v[226:227], v[206:207], v[78:79]
	v_cvt_pk_f32_fp8_sdwa v[208:209], v140 src0_sel:WORD_1
	v_cvt_pk_f32_fp8_sdwa v[210:211], v144 src0_sel:WORD_1
	v_pk_fma_f32 v[224:225], v[208:209], v[80:81], v[224:225]
	v_pk_fma_f32 v[226:227], v[210:211], v[80:81], v[226:227]
	v_cvt_pk_f32_fp8_e32 v[212:213], v141
	v_cvt_pk_f32_fp8_e32 v[214:215], v145
	v_pk_fma_f32 v[224:225], v[212:213], v[82:83], v[224:225]
	v_pk_fma_f32 v[226:227], v[214:215], v[82:83], v[226:227]
	v_cvt_pk_f32_fp8_sdwa v[216:217], v141 src0_sel:WORD_1
	v_cvt_pk_f32_fp8_sdwa v[218:219], v145 src0_sel:WORD_1
	v_pk_fma_f32 v[224:225], v[216:217], v[84:85], v[224:225]
	v_pk_fma_f32 v[226:227], v[218:219], v[84:85], v[226:227]
	v_cvt_pk_f32_fp8_e32 v[204:205], v142
	v_cvt_pk_f32_fp8_e32 v[206:207], v146
	v_pk_fma_f32 v[224:225], v[204:205], v[86:87], v[224:225]
	v_pk_fma_f32 v[226:227], v[206:207], v[86:87], v[226:227]
	v_cvt_pk_f32_fp8_sdwa v[208:209], v142 src0_sel:WORD_1
	v_cvt_pk_f32_fp8_sdwa v[210:211], v146 src0_sel:WORD_1
	v_pk_fma_f32 v[224:225], v[208:209], v[88:89], v[224:225]
	v_pk_fma_f32 v[226:227], v[210:211], v[88:89], v[226:227]
	v_cvt_pk_f32_fp8_e32 v[212:213], v143
	v_cvt_pk_f32_fp8_e32 v[214:215], v147
	v_pk_fma_f32 v[224:225], v[212:213], v[90:91], v[224:225]
	v_pk_fma_f32 v[226:227], v[214:215], v[90:91], v[226:227]
	v_cvt_pk_f32_fp8_sdwa v[216:217], v143 src0_sel:WORD_1
	v_cvt_pk_f32_fp8_sdwa v[218:219], v147 src0_sel:WORD_1
	v_pk_fma_f32 v[224:225], v[216:217], v[92:93], v[224:225]
	v_pk_fma_f32 v[226:227], v[218:219], v[92:93], v[226:227]
	v_add_f32_e32 v110, v220, v221
	v_add_f32_e32 v111, v222, v223
	v_add_f32_e32 v112, v224, v225
	v_add_f32_e32 v113, v226, v227
	v_add_f32_dpp v110, v110, v110 quad_perm:[1,0,3,2] row_mask:0xf bank_mask:0xf
	v_add_f32_dpp v111, v111, v111 quad_perm:[1,0,3,2] row_mask:0xf bank_mask:0xf
	v_add_f32_dpp v112, v112, v112 quad_perm:[1,0,3,2] row_mask:0xf bank_mask:0xf
	v_add_f32_dpp v113, v113, v113 quad_perm:[1,0,3,2] row_mask:0xf bank_mask:0xf
	v_add_f32_dpp v110, v110, v110 quad_perm:[2,3,0,1] row_mask:0xf bank_mask:0xf
	v_add_f32_dpp v111, v111, v111 quad_perm:[2,3,0,1] row_mask:0xf bank_mask:0xf
	v_add_f32_dpp v112, v112, v112 quad_perm:[2,3,0,1] row_mask:0xf bank_mask:0xf
	v_add_f32_dpp v113, v113, v113 quad_perm:[2,3,0,1] row_mask:0xf bank_mask:0xf
	v_add_f32_dpp v110, v110, v110 row_half_mirror row_mask:0xf bank_mask:0xf
	v_add_f32_dpp v111, v111, v111 row_half_mirror row_mask:0xf bank_mask:0xf
	v_add_f32_dpp v112, v112, v112 row_half_mirror row_mask:0xf bank_mask:0xf
	v_add_f32_dpp v113, v113, v113 row_half_mirror row_mask:0xf bank_mask:0xf
	s_waitcnt vmcnt(26)
	v_cvt_pk_f32_fp8_e32 v[204:205], v148
	v_cvt_pk_f32_fp8_e32 v[206:207], v152
	v_pk_mul_f32 v[220:221], v[204:205], v[78:79]
	v_pk_mul_f32 v[222:223], v[206:207], v[78:79]
	v_cvt_pk_f32_fp8_sdwa v[208:209], v148 src0_sel:WORD_1
	v_cvt_pk_f32_fp8_sdwa v[210:211], v152 src0_sel:WORD_1
	v_pk_fma_f32 v[220:221], v[208:209], v[80:81], v[220:221]
	v_pk_fma_f32 v[222:223], v[210:211], v[80:81], v[222:223]
	v_cvt_pk_f32_fp8_e32 v[212:213], v149
	v_cvt_pk_f32_fp8_e32 v[214:215], v153
	v_pk_fma_f32 v[220:221], v[212:213], v[82:83], v[220:221]
	v_pk_fma_f32 v[222:223], v[214:215], v[82:83], v[222:223]
	v_cvt_pk_f32_fp8_sdwa v[216:217], v149 src0_sel:WORD_1
	v_cvt_pk_f32_fp8_sdwa v[218:219], v153 src0_sel:WORD_1
	v_pk_fma_f32 v[220:221], v[216:217], v[84:85], v[220:221]
	v_pk_fma_f32 v[222:223], v[218:219], v[84:85], v[222:223]
	v_cvt_pk_f32_fp8_e32 v[204:205], v150
	v_cvt_pk_f32_fp8_e32 v[206:207], v154
	v_pk_fma_f32 v[220:221], v[204:205], v[86:87], v[220:221]
	v_pk_fma_f32 v[222:223], v[206:207], v[86:87], v[222:223]
	v_cvt_pk_f32_fp8_sdwa v[208:209], v150 src0_sel:WORD_1
	v_cvt_pk_f32_fp8_sdwa v[210:211], v154 src0_sel:WORD_1
	v_pk_fma_f32 v[220:221], v[208:209], v[88:89], v[220:221]
	v_pk_fma_f32 v[222:223], v[210:211], v[88:89], v[222:223]
	v_cvt_pk_f32_fp8_e32 v[212:213], v151
	v_cvt_pk_f32_fp8_e32 v[214:215], v155
	v_pk_fma_f32 v[220:221], v[212:213], v[90:91], v[220:221]
	v_pk_fma_f32 v[222:223], v[214:215], v[90:91], v[222:223]
	v_cvt_pk_f32_fp8_sdwa v[216:217], v151 src0_sel:WORD_1
	v_cvt_pk_f32_fp8_sdwa v[218:219], v155 src0_sel:WORD_1
	v_pk_fma_f32 v[220:221], v[216:217], v[92:93], v[220:221]
	v_pk_fma_f32 v[222:223], v[218:219], v[92:93], v[222:223]
	s_waitcnt vmcnt(24)
; __device__ __forceinline__ void attn_phase(const Args& a, unsigned char* lds, int lane, int wave) {
;     ...
;             float s[8];
; #pragma unroll
;             for (int i = 0; i < 8; ++i) { float kf[16]; unpack16_fp8(kk[i], kf); float d0 = 0.f, d1 = 0.f;
; #pragma unroll
;                 for (int x = 0; x < 16; x += 2) { d0 += q[x] * kf[x]; d1 += q[x + 1] * kf[x + 1]; }
;                 float d = d0 + d1;
;                 d += __shfl_xor(d, 1); d += __shfl_xor(d, 2); d += __shfl_xor(d, 4); s[i] = d; }
	v_cvt_pk_f32_fp8_e32 v[204:205], v156
	v_cvt_pk_f32_fp8_e32 v[206:207], v160
	v_pk_mul_f32 v[224:225], v[204:205], v[78:79]
	v_pk_mul_f32 v[226:227], v[206:207], v[78:79]
	v_cvt_pk_f32_fp8_sdwa v[208:209], v156 src0_sel:WORD_1
	v_cvt_pk_f32_fp8_sdwa v[210:211], v160 src0_sel:WORD_1
	v_pk_fma_f32 v[224:225], v[208:209], v[80:81], v[224:225]
	v_pk_fma_f32 v[226:227], v[210:211], v[80:81], v[226:227]
	v_cvt_pk_f32_fp8_e32 v[212:213], v157
	v_cvt_pk_f32_fp8_e32 v[214:215], v161
	v_pk_fma_f32 v[224:225], v[212:213], v[82:83], v[224:225]
	v_pk_fma_f32 v[226:227], v[214:215], v[82:83], v[226:227]
	v_cvt_pk_f32_fp8_sdwa v[216:217], v157 src0_sel:WORD_1
	v_cvt_pk_f32_fp8_sdwa v[218:219], v161 src0_sel:WORD_1
	v_pk_fma_f32 v[224:225], v[216:217], v[84:85], v[224:225]
	v_pk_fma_f32 v[226:227], v[218:219], v[84:85], v[226:227]
	v_cvt_pk_f32_fp8_e32 v[204:205], v158
	v_cvt_pk_f32_fp8_e32 v[206:207], v162
	v_pk_fma_f32 v[224:225], v[204:205], v[86:87], v[224:225]
	v_pk_fma_f32 v[226:227], v[206:207], v[86:87], v[226:227]
	v_cvt_pk_f32_fp8_sdwa v[208:209], v158 src0_sel:WORD_1
	v_cvt_pk_f32_fp8_sdwa v[210:211], v162 src0_sel:WORD_1
	v_pk_fma_f32 v[224:225], v[208:209], v[88:89], v[224:225]
	v_pk_fma_f32 v[226:227], v[210:211], v[88:89], v[226:227]
	v_cvt_pk_f32_fp8_e32 v[212:213], v159
	v_cvt_pk_f32_fp8_e32 v[214:215], v163
	v_pk_fma_f32 v[224:225], v[212:213], v[90:91], v[224:225]
	v_pk_fma_f32 v[226:227], v[214:215], v[90:91], v[226:227]
	v_cvt_pk_f32_fp8_sdwa v[216:217], v159 src0_sel:WORD_1
	v_cvt_pk_f32_fp8_sdwa v[218:219], v163 src0_sel:WORD_1
	v_pk_fma_f32 v[224:225], v[216:217], v[92:93], v[224:225]
	v_pk_fma_f32 v[226:227], v[218:219], v[92:93], v[226:227]
	v_add_f32_e32 v114, v220, v221
	v_add_f32_e32 v115, v222, v223
	v_add_f32_e32 v116, v224, v225
	v_add_f32_e32 v117, v226, v227
	v_add_f32_dpp v114, v114, v114 quad_perm:[1,0,3,2] row_mask:0xf bank_mask:0xf
	v_add_f32_dpp v115, v115, v115 quad_perm:[1,0,3,2] row_mask:0xf bank_mask:0xf
	v_add_f32_dpp v116, v116, v116 quad_perm:[1,0,3,2] row_mask:0xf bank_mask:0xf
	v_add_f32_dpp v117, v117, v117 quad_perm:[1,0,3,2] row_mask:0xf bank_mask:0xf
	v_add_f32_dpp v114, v114, v114 quad_perm:[2,3,0,1] row_mask:0xf bank_mask:0xf
	v_add_f32_dpp v115, v115, v115 quad_perm:[2,3,0,1] row_mask:0xf bank_mask:0xf
	v_add_f32_dpp v116, v116, v116 quad_perm:[2,3,0,1] row_mask:0xf bank_mask:0xf
	v_add_f32_dpp v117, v117, v117 quad_perm:[2,3,0,1] row_mask:0xf bank_mask:0xf
	v_add_f32_dpp v114, v114, v114 row_half_mirror row_mask:0xf bank_mask:0xf
	v_add_f32_dpp v115, v115, v115 row_half_mirror row_mask:0xf bank_mask:0xf
	v_add_f32_dpp v116, v116, v116 row_half_mirror row_mask:0xf bank_mask:0xf
	v_add_f32_dpp v117, v117, v117 row_half_mirror row_mask:0xf bank_mask:0xf
	s_waitcnt vmcnt(22)
	v_cvt_pk_f32_fp8_e32 v[204:205], v164
	v_cvt_pk_f32_fp8_e32 v[206:207], v168
	v_pk_mul_f32 v[220:221], v[204:205], v[78:79]
	v_pk_mul_f32 v[222:223], v[206:207], v[78:79]
	v_cvt_pk_f32_fp8_sdwa v[208:209], v164 src0_sel:WORD_1
	v_cvt_pk_f32_fp8_sdwa v[210:211], v168 src0_sel:WORD_1
	v_pk_fma_f32 v[220:221], v[208:209], v[80:81], v[220:221]
	v_pk_fma_f32 v[222:223], v[210:211], v[80:81], v[222:223]
	v_cvt_pk_f32_fp8_e32 v[212:213], v165
	v_cvt_pk_f32_fp8_e32 v[214:215], v169
	v_pk_fma_f32 v[220:221], v[212:213], v[82:83], v[220:221]
	v_pk_fma_f32 v[222:223], v[214:215], v[82:83], v[222:223]
	v_cvt_pk_f32_fp8_sdwa v[216:217], v165 src0_sel:WORD_1
	v_cvt_pk_f32_fp8_sdwa v[218:219], v169 src0_sel:WORD_1
	v_pk_fma_f32 v[220:221], v[216:217], v[84:85], v[220:221]
	v_pk_fma_f32 v[222:223], v[218:219], v[84:85], v[222:223]
	v_cvt_pk_f32_fp8_e32 v[204:205], v166
	v_cvt_pk_f32_fp8_e32 v[206:207], v170
	v_pk_fma_f32 v[220:221], v[204:205], v[86:87], v[220:221]
	v_pk_fma_f32 v[222:223], v[206:207], v[86:87], v[222:223]
	v_cvt_pk_f32_fp8_sdwa v[208:209], v166 src0_sel:WORD_1
	v_cvt_pk_f32_fp8_sdwa v[210:211], v170 src0_sel:WORD_1
	v_pk_fma_f32 v[220:221], v[208:209], v[88:89], v[220:221]
	v_pk_fma_f32 v[222:223], v[210:211], v[88:89], v[222:223]
	v_cvt_pk_f32_fp8_e32 v[212:213], v167
	v_cvt_pk_f32_fp8_e32 v[214:215], v171
	v_pk_fma_f32 v[220:221], v[212:213], v[90:91], v[220:221]
	v_pk_fma_f32 v[222:223], v[214:215], v[90:91], v[222:223]
	v_cvt_pk_f32_fp8_sdwa v[216:217], v167 src0_sel:WORD_1
	v_cvt_pk_f32_fp8_sdwa v[218:219], v171 src0_sel:WORD_1
	v_pk_fma_f32 v[220:221], v[216:217], v[92:93], v[220:221]
	v_pk_fma_f32 v[222:223], v[218:219], v[92:93], v[222:223]
	s_waitcnt vmcnt(20)
; __device__ __forceinline__ void attn_phase(const Args& a, unsigned char* lds, int lane, int wave) {
;     ...
;             float s[8];
; #pragma unroll
;             for (int i = 0; i < 8; ++i) { float kf[16]; unpack16_fp8(kk[i], kf); float d0 = 0.f, d1 = 0.f;
; #pragma unroll
;                 for (int x = 0; x < 16; x += 2) { d0 += q[x] * kf[x]; d1 += q[x + 1] * kf[x + 1]; }
;                 float d = d0 + d1;
;                 d += __shfl_xor(d, 1); d += __shfl_xor(d, 2); d += __shfl_xor(d, 4); s[i] = d; }
	v_cvt_pk_f32_fp8_e32 v[204:205], v172
	v_cvt_pk_f32_fp8_e32 v[206:207], v176
	v_pk_mul_f32 v[224:225], v[204:205], v[78:79]
	v_pk_mul_f32 v[226:227], v[206:207], v[78:79]
	v_cvt_pk_f32_fp8_sdwa v[208:209], v172 src0_sel:WORD_1
	v_cvt_pk_f32_fp8_sdwa v[210:211], v176 src0_sel:WORD_1
	v_pk_fma_f32 v[224:225], v[208:209], v[80:81], v[224:225]
	v_pk_fma_f32 v[226:227], v[210:211], v[80:81], v[226:227]
	v_cvt_pk_f32_fp8_e32 v[212:213], v173
	v_cvt_pk_f32_fp8_e32 v[214:215], v177
	v_pk_fma_f32 v[224:225], v[212:213], v[82:83], v[224:225]
	v_pk_fma_f32 v[226:227], v[214:215], v[82:83], v[226:227]
	v_cvt_pk_f32_fp8_sdwa v[216:217], v173 src0_sel:WORD_1
	v_cvt_pk_f32_fp8_sdwa v[218:219], v177 src0_sel:WORD_1
	v_pk_fma_f32 v[224:225], v[216:217], v[84:85], v[224:225]
	v_pk_fma_f32 v[226:227], v[218:219], v[84:85], v[226:227]
	v_cvt_pk_f32_fp8_e32 v[204:205], v174
	v_cvt_pk_f32_fp8_e32 v[206:207], v178
	v_pk_fma_f32 v[224:225], v[204:205], v[86:87], v[224:225]
	v_pk_fma_f32 v[226:227], v[206:207], v[86:87], v[226:227]
	v_cvt_pk_f32_fp8_sdwa v[208:209], v174 src0_sel:WORD_1
	v_cvt_pk_f32_fp8_sdwa v[210:211], v178 src0_sel:WORD_1
	v_pk_fma_f32 v[224:225], v[208:209], v[88:89], v[224:225]
	v_pk_fma_f32 v[226:227], v[210:211], v[88:89], v[226:227]
	v_cvt_pk_f32_fp8_e32 v[212:213], v175
	v_cvt_pk_f32_fp8_e32 v[214:215], v179
	v_pk_fma_f32 v[224:225], v[212:213], v[90:91], v[224:225]
	v_pk_fma_f32 v[226:227], v[214:215], v[90:91], v[226:227]
	v_cvt_pk_f32_fp8_sdwa v[216:217], v175 src0_sel:WORD_1
	v_cvt_pk_f32_fp8_sdwa v[218:219], v179 src0_sel:WORD_1
	v_pk_fma_f32 v[224:225], v[216:217], v[92:93], v[224:225]
	v_pk_fma_f32 v[226:227], v[218:219], v[92:93], v[226:227]
	v_add_f32_e32 v118, v220, v221
	v_add_f32_e32 v119, v222, v223
	v_add_f32_e32 v120, v224, v225
	v_add_f32_e32 v121, v226, v227
	v_add_f32_dpp v118, v118, v118 quad_perm:[1,0,3,2] row_mask:0xf bank_mask:0xf
	v_add_f32_dpp v119, v119, v119 quad_perm:[1,0,3,2] row_mask:0xf bank_mask:0xf
	v_add_f32_dpp v120, v120, v120 quad_perm:[1,0,3,2] row_mask:0xf bank_mask:0xf
	v_add_f32_dpp v121, v121, v121 quad_perm:[1,0,3,2] row_mask:0xf bank_mask:0xf
	v_add_f32_dpp v118, v118, v118 quad_perm:[2,3,0,1] row_mask:0xf bank_mask:0xf
	v_add_f32_dpp v119, v119, v119 quad_perm:[2,3,0,1] row_mask:0xf bank_mask:0xf
	v_add_f32_dpp v120, v120, v120 quad_perm:[2,3,0,1] row_mask:0xf bank_mask:0xf
	v_add_f32_dpp v121, v121, v121 quad_perm:[2,3,0,1] row_mask:0xf bank_mask:0xf
	v_add_f32_dpp v118, v118, v118 row_half_mirror row_mask:0xf bank_mask:0xf
	v_add_f32_dpp v119, v119, v119 row_half_mirror row_mask:0xf bank_mask:0xf
	v_add_f32_dpp v120, v120, v120 row_half_mirror row_mask:0xf bank_mask:0xf
	v_add_f32_dpp v121, v121, v121 row_half_mirror row_mask:0xf bank_mask:0xf
	s_waitcnt vmcnt(18)
	v_cvt_pk_f32_fp8_e32 v[204:205], v180
	v_cvt_pk_f32_fp8_e32 v[206:207], v184
	v_pk_mul_f32 v[220:221], v[204:205], v[78:79]
	v_pk_mul_f32 v[222:223], v[206:207], v[78:79]
	v_cvt_pk_f32_fp8_sdwa v[208:209], v180 src0_sel:WORD_1
	v_cvt_pk_f32_fp8_sdwa v[210:211], v184 src0_sel:WORD_1
	v_pk_fma_f32 v[220:221], v[208:209], v[80:81], v[220:221]
	v_pk_fma_f32 v[222:223], v[210:211], v[80:81], v[222:223]
	v_cvt_pk_f32_fp8_e32 v[212:213], v181
	v_cvt_pk_f32_fp8_e32 v[214:215], v185
	v_pk_fma_f32 v[220:221], v[212:213], v[82:83], v[220:221]
	v_pk_fma_f32 v[222:223], v[214:215], v[82:83], v[222:223]
	v_cvt_pk_f32_fp8_sdwa v[216:217], v181 src0_sel:WORD_1
	v_cvt_pk_f32_fp8_sdwa v[218:219], v185 src0_sel:WORD_1
	v_pk_fma_f32 v[220:221], v[216:217], v[84:85], v[220:221]
	v_pk_fma_f32 v[222:223], v[218:219], v[84:85], v[222:223]
	v_cvt_pk_f32_fp8_e32 v[204:205], v182
	v_cvt_pk_f32_fp8_e32 v[206:207], v186
	v_pk_fma_f32 v[220:221], v[204:205], v[86:87], v[220:221]
	v_pk_fma_f32 v[222:223], v[206:207], v[86:87], v[222:223]
	v_cvt_pk_f32_fp8_sdwa v[208:209], v182 src0_sel:WORD_1
	v_cvt_pk_f32_fp8_sdwa v[210:211], v186 src0_sel:WORD_1
	v_pk_fma_f32 v[220:221], v[208:209], v[88:89], v[220:221]
	v_pk_fma_f32 v[222:223], v[210:211], v[88:89], v[222:223]
	v_cvt_pk_f32_fp8_e32 v[212:213], v183
	v_cvt_pk_f32_fp8_e32 v[214:215], v187
	v_pk_fma_f32 v[220:221], v[212:213], v[90:91], v[220:221]
	v_pk_fma_f32 v[222:223], v[214:215], v[90:91], v[222:223]
	v_cvt_pk_f32_fp8_sdwa v[216:217], v183 src0_sel:WORD_1
	v_cvt_pk_f32_fp8_sdwa v[218:219], v187 src0_sel:WORD_1
	v_pk_fma_f32 v[220:221], v[216:217], v[92:93], v[220:221]
	v_pk_fma_f32 v[222:223], v[218:219], v[92:93], v[222:223]
	s_waitcnt vmcnt(16)
; __device__ __forceinline__ void attn_phase(const Args& a, unsigned char* lds, int lane, int wave) {
;     ...
;             const u32x4 ida = *(const u32x4*)(sel + j), idb = *(const u32x4*)(sel + j + 4);
;     ...
;             for (int i = 0; i < 8; ++i) { float kf[16]; unpack16_fp8(kk[i], kf); float d0 = 0.f, d1 = 0.f;
; #pragma unroll
;                 for (int x = 0; x < 16; x += 2) { d0 += q[x] * kf[x]; d1 += q[x + 1] * kf[x + 1]; }
;                 float d = d0 + d1;
;                 d += __shfl_xor(d, 1); d += __shfl_xor(d, 2); d += __shfl_xor(d, 4); s[i] = d; }
;             const float mn = fmaxf(fmaxf(fmaxf(mx, fmaxf(s[0], s[1])), fmaxf(s[2], s[3])), fmaxf(fmaxf(s[4], s[5]), fmaxf(s[6], s[7])));
;             const float al = __builtin_amdgcn_exp2f(mx - mn);
;             float p[8];
; #pragma unroll
;             for (int i = 0; i < 8; ++i) p[i] = __builtin_amdgcn_exp2f(s[i] - mn);
;             l = l * al + ((p[0] + p[1]) + (p[2] + p[3])) + ((p[4] + p[5]) + (p[6] + p[7]));
; #pragma unroll
;             for (int d = 0; d < 16; ++d) o[d] *= al;
	v_cvt_pk_f32_fp8_e32 v[204:205], v188
	v_cvt_pk_f32_fp8_e32 v[206:207], v192
	v_pk_mul_f32 v[224:225], v[204:205], v[78:79]
	v_pk_mul_f32 v[226:227], v[206:207], v[78:79]
	v_cvt_pk_f32_fp8_sdwa v[208:209], v188 src0_sel:WORD_1
	v_cvt_pk_f32_fp8_sdwa v[210:211], v192 src0_sel:WORD_1
	v_pk_fma_f32 v[224:225], v[208:209], v[80:81], v[224:225]
	v_pk_fma_f32 v[226:227], v[210:211], v[80:81], v[226:227]
	v_cvt_pk_f32_fp8_e32 v[212:213], v189
	v_cvt_pk_f32_fp8_e32 v[214:215], v193
	v_pk_fma_f32 v[224:225], v[212:213], v[82:83], v[224:225]
	v_pk_fma_f32 v[226:227], v[214:215], v[82:83], v[226:227]
	v_cvt_pk_f32_fp8_sdwa v[216:217], v189 src0_sel:WORD_1
	v_cvt_pk_f32_fp8_sdwa v[218:219], v193 src0_sel:WORD_1
	v_pk_fma_f32 v[224:225], v[216:217], v[84:85], v[224:225]
	v_pk_fma_f32 v[226:227], v[218:219], v[84:85], v[226:227]
	v_cvt_pk_f32_fp8_e32 v[204:205], v190
	v_cvt_pk_f32_fp8_e32 v[206:207], v194
	v_pk_fma_f32 v[224:225], v[204:205], v[86:87], v[224:225]
	v_pk_fma_f32 v[226:227], v[206:207], v[86:87], v[226:227]
	v_cvt_pk_f32_fp8_sdwa v[208:209], v190 src0_sel:WORD_1
	v_cvt_pk_f32_fp8_sdwa v[210:211], v194 src0_sel:WORD_1
	v_pk_fma_f32 v[224:225], v[208:209], v[88:89], v[224:225]
	v_pk_fma_f32 v[226:227], v[210:211], v[88:89], v[226:227]
	v_cvt_pk_f32_fp8_e32 v[212:213], v191
	v_cvt_pk_f32_fp8_e32 v[214:215], v195
	v_pk_fma_f32 v[224:225], v[212:213], v[90:91], v[224:225]
	v_pk_fma_f32 v[226:227], v[214:215], v[90:91], v[226:227]
	v_cvt_pk_f32_fp8_sdwa v[216:217], v191 src0_sel:WORD_1
	v_cvt_pk_f32_fp8_sdwa v[218:219], v195 src0_sel:WORD_1
	v_pk_fma_f32 v[224:225], v[216:217], v[92:93], v[224:225]
	v_pk_fma_f32 v[226:227], v[218:219], v[92:93], v[226:227]
	v_add_f32_e32 v122, v220, v221
	v_add_f32_e32 v123, v222, v223
	v_add_f32_e32 v124, v224, v225
	v_add_f32_e32 v125, v226, v227
	v_add_f32_dpp v122, v122, v122 quad_perm:[1,0,3,2] row_mask:0xf bank_mask:0xf
	v_add_f32_dpp v123, v123, v123 quad_perm:[1,0,3,2] row_mask:0xf bank_mask:0xf
	v_add_f32_dpp v124, v124, v124 quad_perm:[1,0,3,2] row_mask:0xf bank_mask:0xf
	v_add_f32_dpp v125, v125, v125 quad_perm:[1,0,3,2] row_mask:0xf bank_mask:0xf
	v_add_f32_dpp v122, v122, v122 quad_perm:[2,3,0,1] row_mask:0xf bank_mask:0xf
	v_add_f32_dpp v123, v123, v123 quad_perm:[2,3,0,1] row_mask:0xf bank_mask:0xf
	v_add_f32_dpp v124, v124, v124 quad_perm:[2,3,0,1] row_mask:0xf bank_mask:0xf
	v_add_f32_dpp v125, v125, v125 quad_perm:[2,3,0,1] row_mask:0xf bank_mask:0xf
	v_add_f32_dpp v122, v122, v122 row_half_mirror row_mask:0xf bank_mask:0xf
	v_add_f32_dpp v123, v123, v123 row_half_mirror row_mask:0xf bank_mask:0xf
	v_add_f32_dpp v124, v124, v124 row_half_mirror row_mask:0xf bank_mask:0xf
	v_add_f32_dpp v125, v125, v125 row_half_mirror row_mask:0xf bank_mask:0xf
	v_max3_f32 v228, v110, v111, v112
	v_max3_f32 v229, v113, v114, v115
	v_max3_f32 v230, v116, v117, v118
	v_max3_f32 v231, v119, v120, v121
	v_max3_f32 v232, v122, v123, v124
	v_max3_f32 v233, v125, v109, v228
	v_max3_f32 v234, v229, v230, v231
	v_max3_f32 v235, v232, v233, v234
	v_sub_f32_e32 v236, v109, v235
	v_sub_f32_e32 v110, v110, v235
	v_sub_f32_e32 v111, v111, v235
	v_sub_f32_e32 v112, v112, v235
	v_sub_f32_e32 v113, v113, v235
	v_sub_f32_e32 v114, v114, v235
	v_sub_f32_e32 v115, v115, v235
	v_sub_f32_e32 v116, v116, v235
	v_sub_f32_e32 v117, v117, v235
	v_sub_f32_e32 v118, v118, v235
	v_sub_f32_e32 v119, v119, v235
	v_sub_f32_e32 v120, v120, v235
	v_sub_f32_e32 v121, v121, v235
	v_sub_f32_e32 v122, v122, v235
	v_sub_f32_e32 v123, v123, v235
	v_sub_f32_e32 v124, v124, v235
	v_sub_f32_e32 v125, v125, v235
	v_exp_f32_e32 v244, v236
	v_exp_f32_e32 v110, v110
	v_exp_f32_e32 v111, v111
	v_exp_f32_e32 v112, v112
	v_exp_f32_e32 v113, v113
	v_exp_f32_e32 v114, v114
	v_exp_f32_e32 v115, v115
	v_exp_f32_e32 v116, v116
	v_exp_f32_e32 v117, v117
	v_exp_f32_e32 v118, v118
	v_exp_f32_e32 v119, v119
	v_exp_f32_e32 v120, v120
	v_exp_f32_e32 v121, v121
	v_exp_f32_e32 v122, v122
	v_exp_f32_e32 v123, v123
	v_exp_f32_e32 v124, v124
	v_exp_f32_e32 v125, v125
	v_mov_b32_e32 v109, v235
	v_pk_mul_f32 v[62:63], v[62:63], v[244:245] op_sel_hi:[1,0]
	v_pk_mul_f32 v[64:65], v[64:65], v[244:245] op_sel_hi:[1,0]
	v_pk_mul_f32 v[66:67], v[66:67], v[244:245] op_sel_hi:[1,0]
	v_pk_mul_f32 v[68:69], v[68:69], v[244:245] op_sel_hi:[1,0]
	v_pk_mul_f32 v[70:71], v[70:71], v[244:245] op_sel_hi:[1,0]
	v_pk_mul_f32 v[72:73], v[72:73], v[244:245] op_sel_hi:[1,0]
	v_pk_mul_f32 v[74:75], v[74:75], v[244:245] op_sel_hi:[1,0]
	v_pk_mul_f32 v[76:77], v[76:77], v[244:245] op_sel_hi:[1,0]
	v_add_f32_e32 v228, v110, v111
	v_add_f32_e32 v229, v112, v113
	v_add_f32_e32 v230, v114, v115
	v_add_f32_e32 v231, v116, v117
	v_add_f32_e32 v232, v118, v119
	v_add_f32_e32 v233, v120, v121
	v_add_f32_e32 v234, v122, v123
	v_add_f32_e32 v235, v124, v125
	v_add_f32_e32 v228, v228, v229
	v_add_f32_e32 v230, v230, v231
	v_add_f32_e32 v232, v232, v233
	v_add_f32_e32 v234, v234, v235
	v_add_f32_e32 v228, v228, v230
	v_add_f32_e32 v232, v232, v234
	v_add_f32_e32 v228, v228, v232
	v_fma_f32 v108, v108, v244, v228
	s_add_i32 s31, s31, 64
	v_mov_b32_e32 v246, s31
	ds_read_b128 v[204:207], v246
	ds_read_b128 v[208:211], v246 offset:16
	ds_read_b128 v[212:215], v246 offset:32
	ds_read_b128 v[216:219], v246 offset:48
	s_waitcnt lgkmcnt(0)
; __device__ __forceinline__ void attn_phase(const Args& a, unsigned char* lds, int lane, int wave) {
;     ...
;             const u32x4 ida = *(const u32x4*)(sel + j), idb = *(const u32x4*)(sel + j + 4);
;             u32x4 kk[8], vv[8];
; #pragma unroll
;             for (int i = 0; i < 8; ++i) { const int idx = (int)(i < 4 ? ida[i & 3] : idb[i & 3]); const unsigned char* kp;
;                 if (!sample) kp = KV8 + (size_t)idx * 2048;
;                 else if (idx < 1024) kp = CKV8 + (size_t)(bb * 1024 + idx) * 2048;
;                 else kp = KV8 + (size_t)(TP + bb * 64 + idx - 1024) * 2048;
;                 kk[i] = *(const u32x4*)(kp + lane * 16); vv[i] = *(const u32x4*)(kp + 1024 + lane * 16); }
;     ...
;             for (int i = 0; i < 8; ++i) { float vf[16]; unpack16_fp8(vv[i], vf);
; #pragma unroll
;                 for (int d = 0; d < 16; ++d) o[d] += p[i] * vf[d]; }
	v_readfirstlane_b32 s8, v204
	v_readfirstlane_b32 s9, v205
	v_readfirstlane_b32 s10, v206
	v_readfirstlane_b32 s11, v207
	v_readfirstlane_b32 s12, v208
	v_readfirstlane_b32 s13, v209
	v_readfirstlane_b32 s14, v210
	v_readfirstlane_b32 s15, v211
	v_readfirstlane_b32 s16, v212
	v_readfirstlane_b32 s17, v213
	v_readfirstlane_b32 s18, v214
	v_readfirstlane_b32 s19, v215
	v_readfirstlane_b32 s20, v216
	v_readfirstlane_b32 s21, v217
	v_readfirstlane_b32 s22, v218
	v_readfirstlane_b32 s23, v219
	s_cmp_lt_u32 s8, 0x400
	s_cselect_b32 s24, s6, s4
	s_cselect_b32 s25, s7, s5
	s_lshl_b32 s8, s8, 11
	s_add_u32 s24, s24, s8
	s_addc_u32 s25, s25, 0
	global_load_dwordx4 v[132:135], v56, s[24:25]
	s_cmp_lt_u32 s9, 0x400
	s_cselect_b32 s24, s6, s4
	s_cselect_b32 s25, s7, s5
	s_lshl_b32 s9, s9, 11
	s_add_u32 s24, s24, s9
	s_addc_u32 s25, s25, 0
	global_load_dwordx4 v[136:139], v56, s[24:25]
	s_cmp_lt_u32 s10, 0x400
	s_cselect_b32 s24, s6, s4
	s_cselect_b32 s25, s7, s5
	s_lshl_b32 s10, s10, 11
	s_add_u32 s24, s24, s10
	s_addc_u32 s25, s25, 0
	global_load_dwordx4 v[140:143], v56, s[24:25]
	s_cmp_lt_u32 s11, 0x400
	s_cselect_b32 s24, s6, s4
	s_cselect_b32 s25, s7, s5
	s_lshl_b32 s11, s11, 11
	s_add_u32 s24, s24, s11
	s_addc_u32 s25, s25, 0
	global_load_dwordx4 v[144:147], v56, s[24:25]
	s_cmp_lt_u32 s12, 0x400
	s_cselect_b32 s24, s6, s4
	s_cselect_b32 s25, s7, s5
	s_lshl_b32 s12, s12, 11
	s_add_u32 s24, s24, s12
	s_addc_u32 s25, s25, 0
	global_load_dwordx4 v[148:151], v56, s[24:25]
	s_cmp_lt_u32 s13, 0x400
	s_cselect_b32 s24, s6, s4
	s_cselect_b32 s25, s7, s5
	s_lshl_b32 s13, s13, 11
	s_add_u32 s24, s24, s13
	s_addc_u32 s25, s25, 0
	global_load_dwordx4 v[152:155], v56, s[24:25]
	s_cmp_lt_u32 s14, 0x400
	s_cselect_b32 s24, s6, s4
	s_cselect_b32 s25, s7, s5
	s_lshl_b32 s14, s14, 11
	s_add_u32 s24, s24, s14
	s_addc_u32 s25, s25, 0
	global_load_dwordx4 v[156:159], v56, s[24:25]
	s_cmp_lt_u32 s15, 0x400
	s_cselect_b32 s24, s6, s4
	s_cselect_b32 s25, s7, s5
	s_lshl_b32 s15, s15, 11
	s_add_u32 s24, s24, s15
	s_addc_u32 s25, s25, 0
	global_load_dwordx4 v[160:163], v56, s[24:25]
	s_cmp_lt_u32 s16, 0x400
	s_cselect_b32 s24, s6, s4
	s_cselect_b32 s25, s7, s5
	s_lshl_b32 s16, s16, 11
	s_add_u32 s24, s24, s16
	s_addc_u32 s25, s25, 0
	global_load_dwordx4 v[164:167], v56, s[24:25]
	s_cmp_lt_u32 s17, 0x400
	s_cselect_b32 s24, s6, s4
	s_cselect_b32 s25, s7, s5
	s_lshl_b32 s17, s17, 11
	s_add_u32 s24, s24, s17
	s_addc_u32 s25, s25, 0
	global_load_dwordx4 v[168:171], v56, s[24:25]
	s_cmp_lt_u32 s18, 0x400
	s_cselect_b32 s24, s6, s4
	s_cselect_b32 s25, s7, s5
	s_lshl_b32 s18, s18, 11
	s_add_u32 s24, s24, s18
	s_addc_u32 s25, s25, 0
	global_load_dwordx4 v[172:175], v56, s[24:25]
	s_cmp_lt_u32 s19, 0x400
	s_cselect_b32 s24, s6, s4
	s_cselect_b32 s25, s7, s5
	s_lshl_b32 s19, s19, 11
	s_add_u32 s24, s24, s19
	s_addc_u32 s25, s25, 0
	global_load_dwordx4 v[176:179], v56, s[24:25]
	s_cmp_lt_u32 s20, 0x400
	s_cselect_b32 s24, s6, s4
	s_cselect_b32 s25, s7, s5
	s_lshl_b32 s20, s20, 11
	s_add_u32 s24, s24, s20
	s_addc_u32 s25, s25, 0
	global_load_dwordx4 v[180:183], v56, s[24:25]
	s_cmp_lt_u32 s21, 0x400
	s_cselect_b32 s24, s6, s4
	s_cselect_b32 s25, s7, s5
	s_lshl_b32 s21, s21, 11
	s_add_u32 s24, s24, s21
	s_addc_u32 s25, s25, 0
	global_load_dwordx4 v[184:187], v56, s[24:25]
	s_cmp_lt_u32 s22, 0x400
	s_cselect_b32 s24, s6, s4
	s_cselect_b32 s25, s7, s5
	s_lshl_b32 s22, s22, 11
	s_add_u32 s24, s24, s22
	s_addc_u32 s25, s25, 0
	global_load_dwordx4 v[188:191], v56, s[24:25]
	s_cmp_lt_u32 s23, 0x400
	s_cselect_b32 s24, s6, s4
	s_cselect_b32 s25, s7, s5
	s_lshl_b32 s23, s23, 11
	s_add_u32 s24, s24, s23
	s_addc_u32 s25, s25, 0
	global_load_dwordx4 v[192:195], v56, s[24:25]
	s_waitcnt vmcnt(31)
	v_cvt_pk_f32_fp8_e32 v[204:205], v0
	v_cvt_pk_f32_fp8_sdwa v[206:207], v0 src0_sel:WORD_1
	v_pk_fma_f32 v[62:63], v[204:205], v[110:111], v[62:63] op_sel_hi:[1,0,1]
	v_pk_fma_f32 v[64:65], v[206:207], v[110:111], v[64:65] op_sel_hi:[1,0,1]
	v_cvt_pk_f32_fp8_e32 v[208:209], v1
	v_cvt_pk_f32_fp8_sdwa v[210:211], v1 src0_sel:WORD_1
	v_pk_fma_f32 v[66:67], v[208:209], v[110:111], v[66:67] op_sel_hi:[1,0,1]
	v_pk_fma_f32 v[68:69], v[210:211], v[110:111], v[68:69] op_sel_hi:[1,0,1]
	v_cvt_pk_f32_fp8_e32 v[212:213], v2
	v_cvt_pk_f32_fp8_sdwa v[214:215], v2 src0_sel:WORD_1
	v_pk_fma_f32 v[70:71], v[212:213], v[110:111], v[70:71] op_sel_hi:[1,0,1]
	v_pk_fma_f32 v[72:73], v[214:215], v[110:111], v[72:73] op_sel_hi:[1,0,1]
	v_cvt_pk_f32_fp8_e32 v[216:217], v3
	v_cvt_pk_f32_fp8_sdwa v[218:219], v3 src0_sel:WORD_1
	v_pk_fma_f32 v[74:75], v[216:217], v[110:111], v[74:75] op_sel_hi:[1,0,1]
	v_pk_fma_f32 v[76:77], v[218:219], v[110:111], v[76:77] op_sel_hi:[1,0,1]
	s_waitcnt vmcnt(30)
	v_cvt_pk_f32_fp8_e32 v[204:205], v4
	v_cvt_pk_f32_fp8_sdwa v[206:207], v4 src0_sel:WORD_1
	v_pk_fma_f32 v[62:63], v[204:205], v[110:111], v[62:63] op_sel:[0,1,0] op_sel_hi:[1,1,1]
	v_pk_fma_f32 v[64:65], v[206:207], v[110:111], v[64:65] op_sel:[0,1,0] op_sel_hi:[1,1,1]
	v_cvt_pk_f32_fp8_e32 v[208:209], v5
	v_cvt_pk_f32_fp8_sdwa v[210:211], v5 src0_sel:WORD_1
	v_pk_fma_f32 v[66:67], v[208:209], v[110:111], v[66:67] op_sel:[0,1,0] op_sel_hi:[1,1,1]
	v_pk_fma_f32 v[68:69], v[210:211], v[110:111], v[68:69] op_sel:[0,1,0] op_sel_hi:[1,1,1]
	v_cvt_pk_f32_fp8_e32 v[212:213], v6
	v_cvt_pk_f32_fp8_sdwa v[214:215], v6 src0_sel:WORD_1
	v_pk_fma_f32 v[70:71], v[212:213], v[110:111], v[70:71] op_sel:[0,1,0] op_sel_hi:[1,1,1]
	v_pk_fma_f32 v[72:73], v[214:215], v[110:111], v[72:73] op_sel:[0,1,0] op_sel_hi:[1,1,1]
	v_cvt_pk_f32_fp8_e32 v[216:217], v7
	v_cvt_pk_f32_fp8_sdwa v[218:219], v7 src0_sel:WORD_1
	v_pk_fma_f32 v[74:75], v[216:217], v[110:111], v[74:75] op_sel:[0,1,0] op_sel_hi:[1,1,1]
	v_pk_fma_f32 v[76:77], v[218:219], v[110:111], v[76:77] op_sel:[0,1,0] op_sel_hi:[1,1,1]
	s_waitcnt vmcnt(29)
; __device__ __forceinline__ void attn_phase(const Args& a, unsigned char* lds, int lane, int wave) {
;     ...
;             for (int i = 0; i < 8; ++i) { float vf[16]; unpack16_fp8(vv[i], vf);
; #pragma unroll
;                 for (int d = 0; d < 16; ++d) o[d] += p[i] * vf[d]; }
	v_cvt_pk_f32_fp8_e32 v[204:205], v8
	v_cvt_pk_f32_fp8_sdwa v[206:207], v8 src0_sel:WORD_1
	v_pk_fma_f32 v[62:63], v[204:205], v[112:113], v[62:63] op_sel_hi:[1,0,1]
	v_pk_fma_f32 v[64:65], v[206:207], v[112:113], v[64:65] op_sel_hi:[1,0,1]
	v_cvt_pk_f32_fp8_e32 v[208:209], v9
	v_cvt_pk_f32_fp8_sdwa v[210:211], v9 src0_sel:WORD_1
	v_pk_fma_f32 v[66:67], v[208:209], v[112:113], v[66:67] op_sel_hi:[1,0,1]
	v_pk_fma_f32 v[68:69], v[210:211], v[112:113], v[68:69] op_sel_hi:[1,0,1]
	v_cvt_pk_f32_fp8_e32 v[212:213], v10
	v_cvt_pk_f32_fp8_sdwa v[214:215], v10 src0_sel:WORD_1
	v_pk_fma_f32 v[70:71], v[212:213], v[112:113], v[70:71] op_sel_hi:[1,0,1]
	v_pk_fma_f32 v[72:73], v[214:215], v[112:113], v[72:73] op_sel_hi:[1,0,1]
	v_cvt_pk_f32_fp8_e32 v[216:217], v11
	v_cvt_pk_f32_fp8_sdwa v[218:219], v11 src0_sel:WORD_1
	v_pk_fma_f32 v[74:75], v[216:217], v[112:113], v[74:75] op_sel_hi:[1,0,1]
	v_pk_fma_f32 v[76:77], v[218:219], v[112:113], v[76:77] op_sel_hi:[1,0,1]
	s_waitcnt vmcnt(28)
	v_cvt_pk_f32_fp8_e32 v[204:205], v12
	v_cvt_pk_f32_fp8_sdwa v[206:207], v12 src0_sel:WORD_1
	v_pk_fma_f32 v[62:63], v[204:205], v[112:113], v[62:63] op_sel:[0,1,0] op_sel_hi:[1,1,1]
	v_pk_fma_f32 v[64:65], v[206:207], v[112:113], v[64:65] op_sel:[0,1,0] op_sel_hi:[1,1,1]
	v_cvt_pk_f32_fp8_e32 v[208:209], v13
	v_cvt_pk_f32_fp8_sdwa v[210:211], v13 src0_sel:WORD_1
	v_pk_fma_f32 v[66:67], v[208:209], v[112:113], v[66:67] op_sel:[0,1,0] op_sel_hi:[1,1,1]
	v_pk_fma_f32 v[68:69], v[210:211], v[112:113], v[68:69] op_sel:[0,1,0] op_sel_hi:[1,1,1]
	v_cvt_pk_f32_fp8_e32 v[212:213], v14
	v_cvt_pk_f32_fp8_sdwa v[214:215], v14 src0_sel:WORD_1
	v_pk_fma_f32 v[70:71], v[212:213], v[112:113], v[70:71] op_sel:[0,1,0] op_sel_hi:[1,1,1]
	v_pk_fma_f32 v[72:73], v[214:215], v[112:113], v[72:73] op_sel:[0,1,0] op_sel_hi:[1,1,1]
	v_cvt_pk_f32_fp8_e32 v[216:217], v15
	v_cvt_pk_f32_fp8_sdwa v[218:219], v15 src0_sel:WORD_1
	v_pk_fma_f32 v[74:75], v[216:217], v[112:113], v[74:75] op_sel:[0,1,0] op_sel_hi:[1,1,1]
	v_pk_fma_f32 v[76:77], v[218:219], v[112:113], v[76:77] op_sel:[0,1,0] op_sel_hi:[1,1,1]
	s_waitcnt vmcnt(27)
	v_cvt_pk_f32_fp8_e32 v[204:205], v16
	v_cvt_pk_f32_fp8_sdwa v[206:207], v16 src0_sel:WORD_1
	v_pk_fma_f32 v[62:63], v[204:205], v[114:115], v[62:63] op_sel_hi:[1,0,1]
	v_pk_fma_f32 v[64:65], v[206:207], v[114:115], v[64:65] op_sel_hi:[1,0,1]
	v_cvt_pk_f32_fp8_e32 v[208:209], v17
	v_cvt_pk_f32_fp8_sdwa v[210:211], v17 src0_sel:WORD_1
	v_pk_fma_f32 v[66:67], v[208:209], v[114:115], v[66:67] op_sel_hi:[1,0,1]
	v_pk_fma_f32 v[68:69], v[210:211], v[114:115], v[68:69] op_sel_hi:[1,0,1]
	v_cvt_pk_f32_fp8_e32 v[212:213], v18
	v_cvt_pk_f32_fp8_sdwa v[214:215], v18 src0_sel:WORD_1
	v_pk_fma_f32 v[70:71], v[212:213], v[114:115], v[70:71] op_sel_hi:[1,0,1]
	v_pk_fma_f32 v[72:73], v[214:215], v[114:115], v[72:73] op_sel_hi:[1,0,1]
	v_cvt_pk_f32_fp8_e32 v[216:217], v19
	v_cvt_pk_f32_fp8_sdwa v[218:219], v19 src0_sel:WORD_1
	v_pk_fma_f32 v[74:75], v[216:217], v[114:115], v[74:75] op_sel_hi:[1,0,1]
	v_pk_fma_f32 v[76:77], v[218:219], v[114:115], v[76:77] op_sel_hi:[1,0,1]
	s_waitcnt vmcnt(26)
	v_cvt_pk_f32_fp8_e32 v[204:205], v20
	v_cvt_pk_f32_fp8_sdwa v[206:207], v20 src0_sel:WORD_1
	v_pk_fma_f32 v[62:63], v[204:205], v[114:115], v[62:63] op_sel:[0,1,0] op_sel_hi:[1,1,1]
	v_pk_fma_f32 v[64:65], v[206:207], v[114:115], v[64:65] op_sel:[0,1,0] op_sel_hi:[1,1,1]
	v_cvt_pk_f32_fp8_e32 v[208:209], v21
	v_cvt_pk_f32_fp8_sdwa v[210:211], v21 src0_sel:WORD_1
	v_pk_fma_f32 v[66:67], v[208:209], v[114:115], v[66:67] op_sel:[0,1,0] op_sel_hi:[1,1,1]
	v_pk_fma_f32 v[68:69], v[210:211], v[114:115], v[68:69] op_sel:[0,1,0] op_sel_hi:[1,1,1]
	v_cvt_pk_f32_fp8_e32 v[212:213], v22
	v_cvt_pk_f32_fp8_sdwa v[214:215], v22 src0_sel:WORD_1
	v_pk_fma_f32 v[70:71], v[212:213], v[114:115], v[70:71] op_sel:[0,1,0] op_sel_hi:[1,1,1]
	v_pk_fma_f32 v[72:73], v[214:215], v[114:115], v[72:73] op_sel:[0,1,0] op_sel_hi:[1,1,1]
	v_cvt_pk_f32_fp8_e32 v[216:217], v23
	v_cvt_pk_f32_fp8_sdwa v[218:219], v23 src0_sel:WORD_1
	v_pk_fma_f32 v[74:75], v[216:217], v[114:115], v[74:75] op_sel:[0,1,0] op_sel_hi:[1,1,1]
	v_pk_fma_f32 v[76:77], v[218:219], v[114:115], v[76:77] op_sel:[0,1,0] op_sel_hi:[1,1,1]
	s_waitcnt vmcnt(25)
	v_cvt_pk_f32_fp8_e32 v[204:205], v24
	v_cvt_pk_f32_fp8_sdwa v[206:207], v24 src0_sel:WORD_1
	v_pk_fma_f32 v[62:63], v[204:205], v[116:117], v[62:63] op_sel_hi:[1,0,1]
	v_pk_fma_f32 v[64:65], v[206:207], v[116:117], v[64:65] op_sel_hi:[1,0,1]
	v_cvt_pk_f32_fp8_e32 v[208:209], v25
	v_cvt_pk_f32_fp8_sdwa v[210:211], v25 src0_sel:WORD_1
	v_pk_fma_f32 v[66:67], v[208:209], v[116:117], v[66:67] op_sel_hi:[1,0,1]
	v_pk_fma_f32 v[68:69], v[210:211], v[116:117], v[68:69] op_sel_hi:[1,0,1]
	v_cvt_pk_f32_fp8_e32 v[212:213], v26
	v_cvt_pk_f32_fp8_sdwa v[214:215], v26 src0_sel:WORD_1
	v_pk_fma_f32 v[70:71], v[212:213], v[116:117], v[70:71] op_sel_hi:[1,0,1]
	v_pk_fma_f32 v[72:73], v[214:215], v[116:117], v[72:73] op_sel_hi:[1,0,1]
	v_cvt_pk_f32_fp8_e32 v[216:217], v27
	v_cvt_pk_f32_fp8_sdwa v[218:219], v27 src0_sel:WORD_1
	v_pk_fma_f32 v[74:75], v[216:217], v[116:117], v[74:75] op_sel_hi:[1,0,1]
	v_pk_fma_f32 v[76:77], v[218:219], v[116:117], v[76:77] op_sel_hi:[1,0,1]
	s_waitcnt vmcnt(24)
; __device__ __forceinline__ void attn_phase(const Args& a, unsigned char* lds, int lane, int wave) {
;     ...
;             for (int i = 0; i < 8; ++i) { float vf[16]; unpack16_fp8(vv[i], vf);
; #pragma unroll
;                 for (int d = 0; d < 16; ++d) o[d] += p[i] * vf[d]; }
	v_cvt_pk_f32_fp8_e32 v[204:205], v28
	v_cvt_pk_f32_fp8_sdwa v[206:207], v28 src0_sel:WORD_1
	v_pk_fma_f32 v[62:63], v[204:205], v[116:117], v[62:63] op_sel:[0,1,0] op_sel_hi:[1,1,1]
	v_pk_fma_f32 v[64:65], v[206:207], v[116:117], v[64:65] op_sel:[0,1,0] op_sel_hi:[1,1,1]
	v_cvt_pk_f32_fp8_e32 v[208:209], v29
	v_cvt_pk_f32_fp8_sdwa v[210:211], v29 src0_sel:WORD_1
	v_pk_fma_f32 v[66:67], v[208:209], v[116:117], v[66:67] op_sel:[0,1,0] op_sel_hi:[1,1,1]
	v_pk_fma_f32 v[68:69], v[210:211], v[116:117], v[68:69] op_sel:[0,1,0] op_sel_hi:[1,1,1]
	v_cvt_pk_f32_fp8_e32 v[212:213], v30
	v_cvt_pk_f32_fp8_sdwa v[214:215], v30 src0_sel:WORD_1
	v_pk_fma_f32 v[70:71], v[212:213], v[116:117], v[70:71] op_sel:[0,1,0] op_sel_hi:[1,1,1]
	v_pk_fma_f32 v[72:73], v[214:215], v[116:117], v[72:73] op_sel:[0,1,0] op_sel_hi:[1,1,1]
	v_cvt_pk_f32_fp8_e32 v[216:217], v31
	v_cvt_pk_f32_fp8_sdwa v[218:219], v31 src0_sel:WORD_1
	v_pk_fma_f32 v[74:75], v[216:217], v[116:117], v[74:75] op_sel:[0,1,0] op_sel_hi:[1,1,1]
	v_pk_fma_f32 v[76:77], v[218:219], v[116:117], v[76:77] op_sel:[0,1,0] op_sel_hi:[1,1,1]
	s_waitcnt vmcnt(23)
	v_cvt_pk_f32_fp8_e32 v[204:205], v32
	v_cvt_pk_f32_fp8_sdwa v[206:207], v32 src0_sel:WORD_1
	v_pk_fma_f32 v[62:63], v[204:205], v[118:119], v[62:63] op_sel_hi:[1,0,1]
	v_pk_fma_f32 v[64:65], v[206:207], v[118:119], v[64:65] op_sel_hi:[1,0,1]
	v_cvt_pk_f32_fp8_e32 v[208:209], v33
	v_cvt_pk_f32_fp8_sdwa v[210:211], v33 src0_sel:WORD_1
	v_pk_fma_f32 v[66:67], v[208:209], v[118:119], v[66:67] op_sel_hi:[1,0,1]
	v_pk_fma_f32 v[68:69], v[210:211], v[118:119], v[68:69] op_sel_hi:[1,0,1]
	v_cvt_pk_f32_fp8_e32 v[212:213], v34
	v_cvt_pk_f32_fp8_sdwa v[214:215], v34 src0_sel:WORD_1
	v_pk_fma_f32 v[70:71], v[212:213], v[118:119], v[70:71] op_sel_hi:[1,0,1]
	v_pk_fma_f32 v[72:73], v[214:215], v[118:119], v[72:73] op_sel_hi:[1,0,1]
	v_cvt_pk_f32_fp8_e32 v[216:217], v35
	v_cvt_pk_f32_fp8_sdwa v[218:219], v35 src0_sel:WORD_1
	v_pk_fma_f32 v[74:75], v[216:217], v[118:119], v[74:75] op_sel_hi:[1,0,1]
	v_pk_fma_f32 v[76:77], v[218:219], v[118:119], v[76:77] op_sel_hi:[1,0,1]
	s_waitcnt vmcnt(22)
	v_cvt_pk_f32_fp8_e32 v[204:205], v36
	v_cvt_pk_f32_fp8_sdwa v[206:207], v36 src0_sel:WORD_1
	v_pk_fma_f32 v[62:63], v[204:205], v[118:119], v[62:63] op_sel:[0,1,0] op_sel_hi:[1,1,1]
	v_pk_fma_f32 v[64:65], v[206:207], v[118:119], v[64:65] op_sel:[0,1,0] op_sel_hi:[1,1,1]
	v_cvt_pk_f32_fp8_e32 v[208:209], v37
	v_cvt_pk_f32_fp8_sdwa v[210:211], v37 src0_sel:WORD_1
	v_pk_fma_f32 v[66:67], v[208:209], v[118:119], v[66:67] op_sel:[0,1,0] op_sel_hi:[1,1,1]
	v_pk_fma_f32 v[68:69], v[210:211], v[118:119], v[68:69] op_sel:[0,1,0] op_sel_hi:[1,1,1]
	v_cvt_pk_f32_fp8_e32 v[212:213], v38
	v_cvt_pk_f32_fp8_sdwa v[214:215], v38 src0_sel:WORD_1
	v_pk_fma_f32 v[70:71], v[212:213], v[118:119], v[70:71] op_sel:[0,1,0] op_sel_hi:[1,1,1]
	v_pk_fma_f32 v[72:73], v[214:215], v[118:119], v[72:73] op_sel:[0,1,0] op_sel_hi:[1,1,1]
	v_cvt_pk_f32_fp8_e32 v[216:217], v39
	v_cvt_pk_f32_fp8_sdwa v[218:219], v39 src0_sel:WORD_1
	v_pk_fma_f32 v[74:75], v[216:217], v[118:119], v[74:75] op_sel:[0,1,0] op_sel_hi:[1,1,1]
	v_pk_fma_f32 v[76:77], v[218:219], v[118:119], v[76:77] op_sel:[0,1,0] op_sel_hi:[1,1,1]
	s_waitcnt vmcnt(21)
	v_cvt_pk_f32_fp8_e32 v[204:205], v40
	v_cvt_pk_f32_fp8_sdwa v[206:207], v40 src0_sel:WORD_1
	v_pk_fma_f32 v[62:63], v[204:205], v[120:121], v[62:63] op_sel_hi:[1,0,1]
	v_pk_fma_f32 v[64:65], v[206:207], v[120:121], v[64:65] op_sel_hi:[1,0,1]
	v_cvt_pk_f32_fp8_e32 v[208:209], v41
	v_cvt_pk_f32_fp8_sdwa v[210:211], v41 src0_sel:WORD_1
	v_pk_fma_f32 v[66:67], v[208:209], v[120:121], v[66:67] op_sel_hi:[1,0,1]
	v_pk_fma_f32 v[68:69], v[210:211], v[120:121], v[68:69] op_sel_hi:[1,0,1]
	v_cvt_pk_f32_fp8_e32 v[212:213], v42
	v_cvt_pk_f32_fp8_sdwa v[214:215], v42 src0_sel:WORD_1
	v_pk_fma_f32 v[70:71], v[212:213], v[120:121], v[70:71] op_sel_hi:[1,0,1]
	v_pk_fma_f32 v[72:73], v[214:215], v[120:121], v[72:73] op_sel_hi:[1,0,1]
	v_cvt_pk_f32_fp8_e32 v[216:217], v43
	v_cvt_pk_f32_fp8_sdwa v[218:219], v43 src0_sel:WORD_1
	v_pk_fma_f32 v[74:75], v[216:217], v[120:121], v[74:75] op_sel_hi:[1,0,1]
	v_pk_fma_f32 v[76:77], v[218:219], v[120:121], v[76:77] op_sel_hi:[1,0,1]
	s_waitcnt vmcnt(20)
	v_cvt_pk_f32_fp8_e32 v[204:205], v44
	v_cvt_pk_f32_fp8_sdwa v[206:207], v44 src0_sel:WORD_1
	v_pk_fma_f32 v[62:63], v[204:205], v[120:121], v[62:63] op_sel:[0,1,0] op_sel_hi:[1,1,1]
	v_pk_fma_f32 v[64:65], v[206:207], v[120:121], v[64:65] op_sel:[0,1,0] op_sel_hi:[1,1,1]
	v_cvt_pk_f32_fp8_e32 v[208:209], v45
	v_cvt_pk_f32_fp8_sdwa v[210:211], v45 src0_sel:WORD_1
	v_pk_fma_f32 v[66:67], v[208:209], v[120:121], v[66:67] op_sel:[0,1,0] op_sel_hi:[1,1,1]
	v_pk_fma_f32 v[68:69], v[210:211], v[120:121], v[68:69] op_sel:[0,1,0] op_sel_hi:[1,1,1]
	v_cvt_pk_f32_fp8_e32 v[212:213], v46
	v_cvt_pk_f32_fp8_sdwa v[214:215], v46 src0_sel:WORD_1
	v_pk_fma_f32 v[70:71], v[212:213], v[120:121], v[70:71] op_sel:[0,1,0] op_sel_hi:[1,1,1]
	v_pk_fma_f32 v[72:73], v[214:215], v[120:121], v[72:73] op_sel:[0,1,0] op_sel_hi:[1,1,1]
	v_cvt_pk_f32_fp8_e32 v[216:217], v47
	v_cvt_pk_f32_fp8_sdwa v[218:219], v47 src0_sel:WORD_1
	v_pk_fma_f32 v[74:75], v[216:217], v[120:121], v[74:75] op_sel:[0,1,0] op_sel_hi:[1,1,1]
	v_pk_fma_f32 v[76:77], v[218:219], v[120:121], v[76:77] op_sel:[0,1,0] op_sel_hi:[1,1,1]
	s_waitcnt vmcnt(19)
; __device__ __forceinline__ void attn_phase(const Args& a, unsigned char* lds, int lane, int wave) {
;     ...
;             for (int i = 0; i < 8; ++i) { const int idx = (int)(i < 4 ? ida[i & 3] : idb[i & 3]); const unsigned char* kp;
;                 if (!sample) kp = KV8 + (size_t)idx * 2048;
;                 else if (idx < 1024) kp = CKV8 + (size_t)(bb * 1024 + idx) * 2048;
;                 else kp = KV8 + (size_t)(TP + bb * 64 + idx - 1024) * 2048;
;                 kk[i] = *(const u32x4*)(kp + lane * 16); vv[i] = *(const u32x4*)(kp + 1024 + lane * 16); }
;     ...
;             for (int i = 0; i < 8; ++i) { float vf[16]; unpack16_fp8(vv[i], vf);
; #pragma unroll
;                 for (int d = 0; d < 16; ++d) o[d] += p[i] * vf[d]; }
	v_cvt_pk_f32_fp8_e32 v[204:205], v48
	v_cvt_pk_f32_fp8_sdwa v[206:207], v48 src0_sel:WORD_1
	v_pk_fma_f32 v[62:63], v[204:205], v[122:123], v[62:63] op_sel_hi:[1,0,1]
	v_pk_fma_f32 v[64:65], v[206:207], v[122:123], v[64:65] op_sel_hi:[1,0,1]
	v_cvt_pk_f32_fp8_e32 v[208:209], v49
	v_cvt_pk_f32_fp8_sdwa v[210:211], v49 src0_sel:WORD_1
	v_pk_fma_f32 v[66:67], v[208:209], v[122:123], v[66:67] op_sel_hi:[1,0,1]
	v_pk_fma_f32 v[68:69], v[210:211], v[122:123], v[68:69] op_sel_hi:[1,0,1]
	v_cvt_pk_f32_fp8_e32 v[212:213], v50
	v_cvt_pk_f32_fp8_sdwa v[214:215], v50 src0_sel:WORD_1
	v_pk_fma_f32 v[70:71], v[212:213], v[122:123], v[70:71] op_sel_hi:[1,0,1]
	v_pk_fma_f32 v[72:73], v[214:215], v[122:123], v[72:73] op_sel_hi:[1,0,1]
	v_cvt_pk_f32_fp8_e32 v[216:217], v51
	v_cvt_pk_f32_fp8_sdwa v[218:219], v51 src0_sel:WORD_1
	v_pk_fma_f32 v[74:75], v[216:217], v[122:123], v[74:75] op_sel_hi:[1,0,1]
	v_pk_fma_f32 v[76:77], v[218:219], v[122:123], v[76:77] op_sel_hi:[1,0,1]
	s_waitcnt vmcnt(18)
	v_cvt_pk_f32_fp8_e32 v[204:205], v52
	v_cvt_pk_f32_fp8_sdwa v[206:207], v52 src0_sel:WORD_1
	v_pk_fma_f32 v[62:63], v[204:205], v[122:123], v[62:63] op_sel:[0,1,0] op_sel_hi:[1,1,1]
	v_pk_fma_f32 v[64:65], v[206:207], v[122:123], v[64:65] op_sel:[0,1,0] op_sel_hi:[1,1,1]
	v_cvt_pk_f32_fp8_e32 v[208:209], v53
	v_cvt_pk_f32_fp8_sdwa v[210:211], v53 src0_sel:WORD_1
	v_pk_fma_f32 v[66:67], v[208:209], v[122:123], v[66:67] op_sel:[0,1,0] op_sel_hi:[1,1,1]
	v_pk_fma_f32 v[68:69], v[210:211], v[122:123], v[68:69] op_sel:[0,1,0] op_sel_hi:[1,1,1]
	v_cvt_pk_f32_fp8_e32 v[212:213], v54
	v_cvt_pk_f32_fp8_sdwa v[214:215], v54 src0_sel:WORD_1
	v_pk_fma_f32 v[70:71], v[212:213], v[122:123], v[70:71] op_sel:[0,1,0] op_sel_hi:[1,1,1]
	v_pk_fma_f32 v[72:73], v[214:215], v[122:123], v[72:73] op_sel:[0,1,0] op_sel_hi:[1,1,1]
	v_cvt_pk_f32_fp8_e32 v[216:217], v55
	v_cvt_pk_f32_fp8_sdwa v[218:219], v55 src0_sel:WORD_1
	v_pk_fma_f32 v[74:75], v[216:217], v[122:123], v[74:75] op_sel:[0,1,0] op_sel_hi:[1,1,1]
	v_pk_fma_f32 v[76:77], v[218:219], v[122:123], v[76:77] op_sel:[0,1,0] op_sel_hi:[1,1,1]
	s_waitcnt vmcnt(17)
	v_cvt_pk_f32_fp8_e32 v[204:205], v196
	v_cvt_pk_f32_fp8_sdwa v[206:207], v196 src0_sel:WORD_1
	v_pk_fma_f32 v[62:63], v[204:205], v[124:125], v[62:63] op_sel_hi:[1,0,1]
	v_pk_fma_f32 v[64:65], v[206:207], v[124:125], v[64:65] op_sel_hi:[1,0,1]
	v_cvt_pk_f32_fp8_e32 v[208:209], v197
	v_cvt_pk_f32_fp8_sdwa v[210:211], v197 src0_sel:WORD_1
	v_pk_fma_f32 v[66:67], v[208:209], v[124:125], v[66:67] op_sel_hi:[1,0,1]
	v_pk_fma_f32 v[68:69], v[210:211], v[124:125], v[68:69] op_sel_hi:[1,0,1]
	v_cvt_pk_f32_fp8_e32 v[212:213], v198
	v_cvt_pk_f32_fp8_sdwa v[214:215], v198 src0_sel:WORD_1
	v_pk_fma_f32 v[70:71], v[212:213], v[124:125], v[70:71] op_sel_hi:[1,0,1]
	v_pk_fma_f32 v[72:73], v[214:215], v[124:125], v[72:73] op_sel_hi:[1,0,1]
	v_cvt_pk_f32_fp8_e32 v[216:217], v199
	v_cvt_pk_f32_fp8_sdwa v[218:219], v199 src0_sel:WORD_1
	v_pk_fma_f32 v[74:75], v[216:217], v[124:125], v[74:75] op_sel_hi:[1,0,1]
	v_pk_fma_f32 v[76:77], v[218:219], v[124:125], v[76:77] op_sel_hi:[1,0,1]
	s_waitcnt vmcnt(16)
	v_cvt_pk_f32_fp8_e32 v[204:205], v200
	v_cvt_pk_f32_fp8_sdwa v[206:207], v200 src0_sel:WORD_1
	v_pk_fma_f32 v[62:63], v[204:205], v[124:125], v[62:63] op_sel:[0,1,0] op_sel_hi:[1,1,1]
	v_pk_fma_f32 v[64:65], v[206:207], v[124:125], v[64:65] op_sel:[0,1,0] op_sel_hi:[1,1,1]
	v_cvt_pk_f32_fp8_e32 v[208:209], v201
	v_cvt_pk_f32_fp8_sdwa v[210:211], v201 src0_sel:WORD_1
	v_pk_fma_f32 v[66:67], v[208:209], v[124:125], v[66:67] op_sel:[0,1,0] op_sel_hi:[1,1,1]
	v_pk_fma_f32 v[68:69], v[210:211], v[124:125], v[68:69] op_sel:[0,1,0] op_sel_hi:[1,1,1]
	v_cvt_pk_f32_fp8_e32 v[212:213], v202
	v_cvt_pk_f32_fp8_sdwa v[214:215], v202 src0_sel:WORD_1
	v_pk_fma_f32 v[70:71], v[212:213], v[124:125], v[70:71] op_sel:[0,1,0] op_sel_hi:[1,1,1]
	v_pk_fma_f32 v[72:73], v[214:215], v[124:125], v[72:73] op_sel:[0,1,0] op_sel_hi:[1,1,1]
	v_cvt_pk_f32_fp8_e32 v[216:217], v203
	v_cvt_pk_f32_fp8_sdwa v[218:219], v203 src0_sel:WORD_1
	v_pk_fma_f32 v[74:75], v[216:217], v[124:125], v[74:75] op_sel:[0,1,0] op_sel_hi:[1,1,1]
	v_pk_fma_f32 v[76:77], v[218:219], v[124:125], v[76:77] op_sel:[0,1,0] op_sel_hi:[1,1,1]
	s_cmp_lt_u32 s8, 0x200000
	s_cselect_b32 s24, s6, s4
	s_cselect_b32 s25, s7, s5
	s_add_u32 s24, s24, s8
	s_addc_u32 s25, s25, 0
	global_load_dwordx4 v[0:3], v56, s[24:25] offset:1024
	s_cmp_lt_u32 s9, 0x200000
	s_cselect_b32 s24, s6, s4
	s_cselect_b32 s25, s7, s5
	s_add_u32 s24, s24, s9
	s_addc_u32 s25, s25, 0
	global_load_dwordx4 v[4:7], v56, s[24:25] offset:1024
	s_cmp_lt_u32 s10, 0x200000
	s_cselect_b32 s24, s6, s4
	s_cselect_b32 s25, s7, s5
	s_add_u32 s24, s24, s10
	s_addc_u32 s25, s25, 0
	global_load_dwordx4 v[8:11], v56, s[24:25] offset:1024
	s_cmp_lt_u32 s11, 0x200000
	s_cselect_b32 s24, s6, s4
	s_cselect_b32 s25, s7, s5
	s_add_u32 s24, s24, s11
	s_addc_u32 s25, s25, 0
	global_load_dwordx4 v[12:15], v56, s[24:25] offset:1024
	s_cmp_lt_u32 s12, 0x200000
	s_cselect_b32 s24, s6, s4
	s_cselect_b32 s25, s7, s5
	s_add_u32 s24, s24, s12
	s_addc_u32 s25, s25, 0
	global_load_dwordx4 v[16:19], v56, s[24:25] offset:1024
	s_cmp_lt_u32 s13, 0x200000
	s_cselect_b32 s24, s6, s4
	s_cselect_b32 s25, s7, s5
	s_add_u32 s24, s24, s13
	s_addc_u32 s25, s25, 0
	global_load_dwordx4 v[20:23], v56, s[24:25] offset:1024
	s_cmp_lt_u32 s14, 0x200000
	s_cselect_b32 s24, s6, s4
	s_cselect_b32 s25, s7, s5
	s_add_u32 s24, s24, s14
	s_addc_u32 s25, s25, 0
	global_load_dwordx4 v[24:27], v56, s[24:25] offset:1024
	s_cmp_lt_u32 s15, 0x200000
	s_cselect_b32 s24, s6, s4
	s_cselect_b32 s25, s7, s5
	s_add_u32 s24, s24, s15
	s_addc_u32 s25, s25, 0
; __device__ __forceinline__ void attn_phase(const Args& a, unsigned char* lds, int lane, int wave) {
;     ...
;             for (int i = 0; i < 8; ++i) { const int idx = (int)(i < 4 ? ida[i & 3] : idb[i & 3]); const unsigned char* kp;
;                 if (!sample) kp = KV8 + (size_t)idx * 2048;
;                 else if (idx < 1024) kp = CKV8 + (size_t)(bb * 1024 + idx) * 2048;
;                 else kp = KV8 + (size_t)(TP + bb * 64 + idx - 1024) * 2048;
;                 kk[i] = *(const u32x4*)(kp + lane * 16); vv[i] = *(const u32x4*)(kp + 1024 + lane * 16); }
;     ...
;             for (int i = 0; i < 8; ++i) { float kf[16]; unpack16_fp8(kk[i], kf); float d0 = 0.f, d1 = 0.f;
; #pragma unroll
;                 for (int x = 0; x < 16; x += 2) { d0 += q[x] * kf[x]; d1 += q[x + 1] * kf[x + 1]; }
;                 float d = d0 + d1;
;                 d += __shfl_xor(d, 1); d += __shfl_xor(d, 2); d += __shfl_xor(d, 4); s[i] = d; }
	global_load_dwordx4 v[28:31], v56, s[24:25] offset:1024
	s_cmp_lt_u32 s16, 0x200000
	s_cselect_b32 s24, s6, s4
	s_cselect_b32 s25, s7, s5
	s_add_u32 s24, s24, s16
	s_addc_u32 s25, s25, 0
	global_load_dwordx4 v[32:35], v56, s[24:25] offset:1024
	s_cmp_lt_u32 s17, 0x200000
	s_cselect_b32 s24, s6, s4
	s_cselect_b32 s25, s7, s5
	s_add_u32 s24, s24, s17
	s_addc_u32 s25, s25, 0
	global_load_dwordx4 v[36:39], v56, s[24:25] offset:1024
	s_cmp_lt_u32 s18, 0x200000
	s_cselect_b32 s24, s6, s4
	s_cselect_b32 s25, s7, s5
	s_add_u32 s24, s24, s18
	s_addc_u32 s25, s25, 0
	global_load_dwordx4 v[40:43], v56, s[24:25] offset:1024
	s_cmp_lt_u32 s19, 0x200000
	s_cselect_b32 s24, s6, s4
	s_cselect_b32 s25, s7, s5
	s_add_u32 s24, s24, s19
	s_addc_u32 s25, s25, 0
	global_load_dwordx4 v[44:47], v56, s[24:25] offset:1024
	s_cmp_lt_u32 s20, 0x200000
	s_cselect_b32 s24, s6, s4
	s_cselect_b32 s25, s7, s5
	s_add_u32 s24, s24, s20
	s_addc_u32 s25, s25, 0
	global_load_dwordx4 v[48:51], v56, s[24:25] offset:1024
	s_cmp_lt_u32 s21, 0x200000
	s_cselect_b32 s24, s6, s4
	s_cselect_b32 s25, s7, s5
	s_add_u32 s24, s24, s21
	s_addc_u32 s25, s25, 0
	global_load_dwordx4 v[52:55], v56, s[24:25] offset:1024
	s_cmp_lt_u32 s22, 0x200000
	s_cselect_b32 s24, s6, s4
	s_cselect_b32 s25, s7, s5
	s_add_u32 s24, s24, s22
	s_addc_u32 s25, s25, 0
	global_load_dwordx4 v[196:199], v56, s[24:25] offset:1024
	s_cmp_lt_u32 s23, 0x200000
	s_cselect_b32 s24, s6, s4
	s_cselect_b32 s25, s7, s5
	s_add_u32 s24, s24, s23
	s_addc_u32 s25, s25, 0
	global_load_dwordx4 v[200:203], v56, s[24:25] offset:1024
	s_add_i32 s3, s3, -1
	s_cmp_lg_u32 s3, 0
	s_cbranch_scc1 .Lat_blk
	s_waitcnt vmcnt(30)
	v_cvt_pk_f32_fp8_e32 v[204:205], v132
	v_cvt_pk_f32_fp8_e32 v[206:207], v136
	v_pk_mul_f32 v[220:221], v[204:205], v[78:79]
	v_pk_mul_f32 v[222:223], v[206:207], v[78:79]
	v_cvt_pk_f32_fp8_sdwa v[208:209], v132 src0_sel:WORD_1
	v_cvt_pk_f32_fp8_sdwa v[210:211], v136 src0_sel:WORD_1
	v_pk_fma_f32 v[220:221], v[208:209], v[80:81], v[220:221]
	v_pk_fma_f32 v[222:223], v[210:211], v[80:81], v[222:223]
	v_cvt_pk_f32_fp8_e32 v[212:213], v133
	v_cvt_pk_f32_fp8_e32 v[214:215], v137
	v_pk_fma_f32 v[220:221], v[212:213], v[82:83], v[220:221]
	v_pk_fma_f32 v[222:223], v[214:215], v[82:83], v[222:223]
	v_cvt_pk_f32_fp8_sdwa v[216:217], v133 src0_sel:WORD_1
	v_cvt_pk_f32_fp8_sdwa v[218:219], v137 src0_sel:WORD_1
	v_pk_fma_f32 v[220:221], v[216:217], v[84:85], v[220:221]
	v_pk_fma_f32 v[222:223], v[218:219], v[84:85], v[222:223]
	v_cvt_pk_f32_fp8_e32 v[204:205], v134
	v_cvt_pk_f32_fp8_e32 v[206:207], v138
	v_pk_fma_f32 v[220:221], v[204:205], v[86:87], v[220:221]
	v_pk_fma_f32 v[222:223], v[206:207], v[86:87], v[222:223]
	v_cvt_pk_f32_fp8_sdwa v[208:209], v134 src0_sel:WORD_1
	v_cvt_pk_f32_fp8_sdwa v[210:211], v138 src0_sel:WORD_1
	v_pk_fma_f32 v[220:221], v[208:209], v[88:89], v[220:221]
	v_pk_fma_f32 v[222:223], v[210:211], v[88:89], v[222:223]
	v_cvt_pk_f32_fp8_e32 v[212:213], v135
	v_cvt_pk_f32_fp8_e32 v[214:215], v139
	v_pk_fma_f32 v[220:221], v[212:213], v[90:91], v[220:221]
	v_pk_fma_f32 v[222:223], v[214:215], v[90:91], v[222:223]
	v_cvt_pk_f32_fp8_sdwa v[216:217], v135 src0_sel:WORD_1
	v_cvt_pk_f32_fp8_sdwa v[218:219], v139 src0_sel:WORD_1
	v_pk_fma_f32 v[220:221], v[216:217], v[92:93], v[220:221]
	v_pk_fma_f32 v[222:223], v[218:219], v[92:93], v[222:223]
	s_waitcnt vmcnt(28)
	v_cvt_pk_f32_fp8_e32 v[204:205], v140
	v_cvt_pk_f32_fp8_e32 v[206:207], v144
	v_pk_mul_f32 v[224:225], v[204:205], v[78:79]
	v_pk_mul_f32 v[226:227], v[206:207], v[78:79]
	v_cvt_pk_f32_fp8_sdwa v[208:209], v140 src0_sel:WORD_1
	v_cvt_pk_f32_fp8_sdwa v[210:211], v144 src0_sel:WORD_1
	v_pk_fma_f32 v[224:225], v[208:209], v[80:81], v[224:225]
	v_pk_fma_f32 v[226:227], v[210:211], v[80:81], v[226:227]
	v_cvt_pk_f32_fp8_e32 v[212:213], v141
	v_cvt_pk_f32_fp8_e32 v[214:215], v145
	v_pk_fma_f32 v[224:225], v[212:213], v[82:83], v[224:225]
	v_pk_fma_f32 v[226:227], v[214:215], v[82:83], v[226:227]
	v_cvt_pk_f32_fp8_sdwa v[216:217], v141 src0_sel:WORD_1
	v_cvt_pk_f32_fp8_sdwa v[218:219], v145 src0_sel:WORD_1
	v_pk_fma_f32 v[224:225], v[216:217], v[84:85], v[224:225]
	v_pk_fma_f32 v[226:227], v[218:219], v[84:85], v[226:227]
	v_cvt_pk_f32_fp8_e32 v[204:205], v142
	v_cvt_pk_f32_fp8_e32 v[206:207], v146
	v_pk_fma_f32 v[224:225], v[204:205], v[86:87], v[224:225]
	v_pk_fma_f32 v[226:227], v[206:207], v[86:87], v[226:227]
	v_cvt_pk_f32_fp8_sdwa v[208:209], v142 src0_sel:WORD_1
	v_cvt_pk_f32_fp8_sdwa v[210:211], v146 src0_sel:WORD_1
	v_pk_fma_f32 v[224:225], v[208:209], v[88:89], v[224:225]
	v_pk_fma_f32 v[226:227], v[210:211], v[88:89], v[226:227]
	v_cvt_pk_f32_fp8_e32 v[212:213], v143
	v_cvt_pk_f32_fp8_e32 v[214:215], v147
	v_pk_fma_f32 v[224:225], v[212:213], v[90:91], v[224:225]
	v_pk_fma_f32 v[226:227], v[214:215], v[90:91], v[226:227]
	v_cvt_pk_f32_fp8_sdwa v[216:217], v143 src0_sel:WORD_1
	v_cvt_pk_f32_fp8_sdwa v[218:219], v147 src0_sel:WORD_1
	v_pk_fma_f32 v[224:225], v[216:217], v[92:93], v[224:225]
	v_pk_fma_f32 v[226:227], v[218:219], v[92:93], v[226:227]
	v_add_f32_e32 v110, v220, v221
	v_add_f32_e32 v111, v222, v223
	v_add_f32_e32 v112, v224, v225
	v_add_f32_e32 v113, v226, v227
	v_add_f32_dpp v110, v110, v110 quad_perm:[1,0,3,2] row_mask:0xf bank_mask:0xf
	v_add_f32_dpp v111, v111, v111 quad_perm:[1,0,3,2] row_mask:0xf bank_mask:0xf
	v_add_f32_dpp v112, v112, v112 quad_perm:[1,0,3,2] row_mask:0xf bank_mask:0xf
	v_add_f32_dpp v113, v113, v113 quad_perm:[1,0,3,2] row_mask:0xf bank_mask:0xf
	v_add_f32_dpp v110, v110, v110 quad_perm:[2,3,0,1] row_mask:0xf bank_mask:0xf
	v_add_f32_dpp v111, v111, v111 quad_perm:[2,3,0,1] row_mask:0xf bank_mask:0xf
	v_add_f32_dpp v112, v112, v112 quad_perm:[2,3,0,1] row_mask:0xf bank_mask:0xf
	v_add_f32_dpp v113, v113, v113 quad_perm:[2,3,0,1] row_mask:0xf bank_mask:0xf
	v_add_f32_dpp v110, v110, v110 row_half_mirror row_mask:0xf bank_mask:0xf
	v_add_f32_dpp v111, v111, v111 row_half_mirror row_mask:0xf bank_mask:0xf
	v_add_f32_dpp v112, v112, v112 row_half_mirror row_mask:0xf bank_mask:0xf
	v_add_f32_dpp v113, v113, v113 row_half_mirror row_mask:0xf bank_mask:0xf
	s_waitcnt vmcnt(26)
; __device__ __forceinline__ void attn_phase(const Args& a, unsigned char* lds, int lane, int wave) {
;     ...
;             for (int i = 0; i < 8; ++i) { float kf[16]; unpack16_fp8(kk[i], kf); float d0 = 0.f, d1 = 0.f;
; #pragma unroll
;                 for (int x = 0; x < 16; x += 2) { d0 += q[x] * kf[x]; d1 += q[x + 1] * kf[x + 1]; }
;                 float d = d0 + d1;
;                 d += __shfl_xor(d, 1); d += __shfl_xor(d, 2); d += __shfl_xor(d, 4); s[i] = d; }
	v_cvt_pk_f32_fp8_e32 v[204:205], v148
	v_cvt_pk_f32_fp8_e32 v[206:207], v152
	v_pk_mul_f32 v[220:221], v[204:205], v[78:79]
	v_pk_mul_f32 v[222:223], v[206:207], v[78:79]
	v_cvt_pk_f32_fp8_sdwa v[208:209], v148 src0_sel:WORD_1
	v_cvt_pk_f32_fp8_sdwa v[210:211], v152 src0_sel:WORD_1
	v_pk_fma_f32 v[220:221], v[208:209], v[80:81], v[220:221]
	v_pk_fma_f32 v[222:223], v[210:211], v[80:81], v[222:223]
	v_cvt_pk_f32_fp8_e32 v[212:213], v149
	v_cvt_pk_f32_fp8_e32 v[214:215], v153
	v_pk_fma_f32 v[220:221], v[212:213], v[82:83], v[220:221]
	v_pk_fma_f32 v[222:223], v[214:215], v[82:83], v[222:223]
	v_cvt_pk_f32_fp8_sdwa v[216:217], v149 src0_sel:WORD_1
	v_cvt_pk_f32_fp8_sdwa v[218:219], v153 src0_sel:WORD_1
	v_pk_fma_f32 v[220:221], v[216:217], v[84:85], v[220:221]
	v_pk_fma_f32 v[222:223], v[218:219], v[84:85], v[222:223]
	v_cvt_pk_f32_fp8_e32 v[204:205], v150
	v_cvt_pk_f32_fp8_e32 v[206:207], v154
	v_pk_fma_f32 v[220:221], v[204:205], v[86:87], v[220:221]
	v_pk_fma_f32 v[222:223], v[206:207], v[86:87], v[222:223]
	v_cvt_pk_f32_fp8_sdwa v[208:209], v150 src0_sel:WORD_1
	v_cvt_pk_f32_fp8_sdwa v[210:211], v154 src0_sel:WORD_1
	v_pk_fma_f32 v[220:221], v[208:209], v[88:89], v[220:221]
	v_pk_fma_f32 v[222:223], v[210:211], v[88:89], v[222:223]
	v_cvt_pk_f32_fp8_e32 v[212:213], v151
	v_cvt_pk_f32_fp8_e32 v[214:215], v155
	v_pk_fma_f32 v[220:221], v[212:213], v[90:91], v[220:221]
	v_pk_fma_f32 v[222:223], v[214:215], v[90:91], v[222:223]
	v_cvt_pk_f32_fp8_sdwa v[216:217], v151 src0_sel:WORD_1
	v_cvt_pk_f32_fp8_sdwa v[218:219], v155 src0_sel:WORD_1
	v_pk_fma_f32 v[220:221], v[216:217], v[92:93], v[220:221]
	v_pk_fma_f32 v[222:223], v[218:219], v[92:93], v[222:223]
	s_waitcnt vmcnt(24)
	v_cvt_pk_f32_fp8_e32 v[204:205], v156
	v_cvt_pk_f32_fp8_e32 v[206:207], v160
	v_pk_mul_f32 v[224:225], v[204:205], v[78:79]
	v_pk_mul_f32 v[226:227], v[206:207], v[78:79]
	v_cvt_pk_f32_fp8_sdwa v[208:209], v156 src0_sel:WORD_1
	v_cvt_pk_f32_fp8_sdwa v[210:211], v160 src0_sel:WORD_1
	v_pk_fma_f32 v[224:225], v[208:209], v[80:81], v[224:225]
	v_pk_fma_f32 v[226:227], v[210:211], v[80:81], v[226:227]
	v_cvt_pk_f32_fp8_e32 v[212:213], v157
	v_cvt_pk_f32_fp8_e32 v[214:215], v161
	v_pk_fma_f32 v[224:225], v[212:213], v[82:83], v[224:225]
	v_pk_fma_f32 v[226:227], v[214:215], v[82:83], v[226:227]
	v_cvt_pk_f32_fp8_sdwa v[216:217], v157 src0_sel:WORD_1
	v_cvt_pk_f32_fp8_sdwa v[218:219], v161 src0_sel:WORD_1
	v_pk_fma_f32 v[224:225], v[216:217], v[84:85], v[224:225]
	v_pk_fma_f32 v[226:227], v[218:219], v[84:85], v[226:227]
	v_cvt_pk_f32_fp8_e32 v[204:205], v158
	v_cvt_pk_f32_fp8_e32 v[206:207], v162
	v_pk_fma_f32 v[224:225], v[204:205], v[86:87], v[224:225]
	v_pk_fma_f32 v[226:227], v[206:207], v[86:87], v[226:227]
	v_cvt_pk_f32_fp8_sdwa v[208:209], v158 src0_sel:WORD_1
	v_cvt_pk_f32_fp8_sdwa v[210:211], v162 src0_sel:WORD_1
	v_pk_fma_f32 v[224:225], v[208:209], v[88:89], v[224:225]
	v_pk_fma_f32 v[226:227], v[210:211], v[88:89], v[226:227]
	v_cvt_pk_f32_fp8_e32 v[212:213], v159
	v_cvt_pk_f32_fp8_e32 v[214:215], v163
	v_pk_fma_f32 v[224:225], v[212:213], v[90:91], v[224:225]
	v_pk_fma_f32 v[226:227], v[214:215], v[90:91], v[226:227]
	v_cvt_pk_f32_fp8_sdwa v[216:217], v159 src0_sel:WORD_1
	v_cvt_pk_f32_fp8_sdwa v[218:219], v163 src0_sel:WORD_1
	v_pk_fma_f32 v[224:225], v[216:217], v[92:93], v[224:225]
	v_pk_fma_f32 v[226:227], v[218:219], v[92:93], v[226:227]
	v_add_f32_e32 v114, v220, v221
	v_add_f32_e32 v115, v222, v223
	v_add_f32_e32 v116, v224, v225
	v_add_f32_e32 v117, v226, v227
	v_add_f32_dpp v114, v114, v114 quad_perm:[1,0,3,2] row_mask:0xf bank_mask:0xf
	v_add_f32_dpp v115, v115, v115 quad_perm:[1,0,3,2] row_mask:0xf bank_mask:0xf
	v_add_f32_dpp v116, v116, v116 quad_perm:[1,0,3,2] row_mask:0xf bank_mask:0xf
	v_add_f32_dpp v117, v117, v117 quad_perm:[1,0,3,2] row_mask:0xf bank_mask:0xf
	v_add_f32_dpp v114, v114, v114 quad_perm:[2,3,0,1] row_mask:0xf bank_mask:0xf
	v_add_f32_dpp v115, v115, v115 quad_perm:[2,3,0,1] row_mask:0xf bank_mask:0xf
	v_add_f32_dpp v116, v116, v116 quad_perm:[2,3,0,1] row_mask:0xf bank_mask:0xf
	v_add_f32_dpp v117, v117, v117 quad_perm:[2,3,0,1] row_mask:0xf bank_mask:0xf
	v_add_f32_dpp v114, v114, v114 row_half_mirror row_mask:0xf bank_mask:0xf
	v_add_f32_dpp v115, v115, v115 row_half_mirror row_mask:0xf bank_mask:0xf
	v_add_f32_dpp v116, v116, v116 row_half_mirror row_mask:0xf bank_mask:0xf
	v_add_f32_dpp v117, v117, v117 row_half_mirror row_mask:0xf bank_mask:0xf
	s_waitcnt vmcnt(22)
	v_cvt_pk_f32_fp8_e32 v[204:205], v164
	v_cvt_pk_f32_fp8_e32 v[206:207], v168
	v_pk_mul_f32 v[220:221], v[204:205], v[78:79]
	v_pk_mul_f32 v[222:223], v[206:207], v[78:79]
	v_cvt_pk_f32_fp8_sdwa v[208:209], v164 src0_sel:WORD_1
	v_cvt_pk_f32_fp8_sdwa v[210:211], v168 src0_sel:WORD_1
	v_pk_fma_f32 v[220:221], v[208:209], v[80:81], v[220:221]
	v_pk_fma_f32 v[222:223], v[210:211], v[80:81], v[222:223]
	v_cvt_pk_f32_fp8_e32 v[212:213], v165
	v_cvt_pk_f32_fp8_e32 v[214:215], v169
	v_pk_fma_f32 v[220:221], v[212:213], v[82:83], v[220:221]
	v_pk_fma_f32 v[222:223], v[214:215], v[82:83], v[222:223]
	v_cvt_pk_f32_fp8_sdwa v[216:217], v165 src0_sel:WORD_1
	v_cvt_pk_f32_fp8_sdwa v[218:219], v169 src0_sel:WORD_1
	v_pk_fma_f32 v[220:221], v[216:217], v[84:85], v[220:221]
	v_pk_fma_f32 v[222:223], v[218:219], v[84:85], v[222:223]
	v_cvt_pk_f32_fp8_e32 v[204:205], v166
	v_cvt_pk_f32_fp8_e32 v[206:207], v170
	v_pk_fma_f32 v[220:221], v[204:205], v[86:87], v[220:221]
	v_pk_fma_f32 v[222:223], v[206:207], v[86:87], v[222:223]
	v_cvt_pk_f32_fp8_sdwa v[208:209], v166 src0_sel:WORD_1
	v_cvt_pk_f32_fp8_sdwa v[210:211], v170 src0_sel:WORD_1
	v_pk_fma_f32 v[220:221], v[208:209], v[88:89], v[220:221]
	v_pk_fma_f32 v[222:223], v[210:211], v[88:89], v[222:223]
	v_cvt_pk_f32_fp8_e32 v[212:213], v167
	v_cvt_pk_f32_fp8_e32 v[214:215], v171
	v_pk_fma_f32 v[220:221], v[212:213], v[90:91], v[220:221]
	v_pk_fma_f32 v[222:223], v[214:215], v[90:91], v[222:223]
	v_cvt_pk_f32_fp8_sdwa v[216:217], v167 src0_sel:WORD_1
	v_cvt_pk_f32_fp8_sdwa v[218:219], v171 src0_sel:WORD_1
	v_pk_fma_f32 v[220:221], v[216:217], v[92:93], v[220:221]
	v_pk_fma_f32 v[222:223], v[218:219], v[92:93], v[222:223]
	s_waitcnt vmcnt(20)
; __device__ __forceinline__ void attn_phase(const Args& a, unsigned char* lds, int lane, int wave) {
;     ...
;             for (int i = 0; i < 8; ++i) { float kf[16]; unpack16_fp8(kk[i], kf); float d0 = 0.f, d1 = 0.f;
; #pragma unroll
;                 for (int x = 0; x < 16; x += 2) { d0 += q[x] * kf[x]; d1 += q[x + 1] * kf[x + 1]; }
;                 float d = d0 + d1;
;                 d += __shfl_xor(d, 1); d += __shfl_xor(d, 2); d += __shfl_xor(d, 4); s[i] = d; }
	v_cvt_pk_f32_fp8_e32 v[204:205], v172
	v_cvt_pk_f32_fp8_e32 v[206:207], v176
	v_pk_mul_f32 v[224:225], v[204:205], v[78:79]
	v_pk_mul_f32 v[226:227], v[206:207], v[78:79]
	v_cvt_pk_f32_fp8_sdwa v[208:209], v172 src0_sel:WORD_1
	v_cvt_pk_f32_fp8_sdwa v[210:211], v176 src0_sel:WORD_1
	v_pk_fma_f32 v[224:225], v[208:209], v[80:81], v[224:225]
	v_pk_fma_f32 v[226:227], v[210:211], v[80:81], v[226:227]
	v_cvt_pk_f32_fp8_e32 v[212:213], v173
	v_cvt_pk_f32_fp8_e32 v[214:215], v177
	v_pk_fma_f32 v[224:225], v[212:213], v[82:83], v[224:225]
	v_pk_fma_f32 v[226:227], v[214:215], v[82:83], v[226:227]
	v_cvt_pk_f32_fp8_sdwa v[216:217], v173 src0_sel:WORD_1
	v_cvt_pk_f32_fp8_sdwa v[218:219], v177 src0_sel:WORD_1
	v_pk_fma_f32 v[224:225], v[216:217], v[84:85], v[224:225]
	v_pk_fma_f32 v[226:227], v[218:219], v[84:85], v[226:227]
	v_cvt_pk_f32_fp8_e32 v[204:205], v174
	v_cvt_pk_f32_fp8_e32 v[206:207], v178
	v_pk_fma_f32 v[224:225], v[204:205], v[86:87], v[224:225]
	v_pk_fma_f32 v[226:227], v[206:207], v[86:87], v[226:227]
	v_cvt_pk_f32_fp8_sdwa v[208:209], v174 src0_sel:WORD_1
	v_cvt_pk_f32_fp8_sdwa v[210:211], v178 src0_sel:WORD_1
	v_pk_fma_f32 v[224:225], v[208:209], v[88:89], v[224:225]
	v_pk_fma_f32 v[226:227], v[210:211], v[88:89], v[226:227]
	v_cvt_pk_f32_fp8_e32 v[212:213], v175
	v_cvt_pk_f32_fp8_e32 v[214:215], v179
	v_pk_fma_f32 v[224:225], v[212:213], v[90:91], v[224:225]
	v_pk_fma_f32 v[226:227], v[214:215], v[90:91], v[226:227]
	v_cvt_pk_f32_fp8_sdwa v[216:217], v175 src0_sel:WORD_1
	v_cvt_pk_f32_fp8_sdwa v[218:219], v179 src0_sel:WORD_1
	v_pk_fma_f32 v[224:225], v[216:217], v[92:93], v[224:225]
	v_pk_fma_f32 v[226:227], v[218:219], v[92:93], v[226:227]
	v_add_f32_e32 v118, v220, v221
	v_add_f32_e32 v119, v222, v223
	v_add_f32_e32 v120, v224, v225
	v_add_f32_e32 v121, v226, v227
	v_add_f32_dpp v118, v118, v118 quad_perm:[1,0,3,2] row_mask:0xf bank_mask:0xf
	v_add_f32_dpp v119, v119, v119 quad_perm:[1,0,3,2] row_mask:0xf bank_mask:0xf
	v_add_f32_dpp v120, v120, v120 quad_perm:[1,0,3,2] row_mask:0xf bank_mask:0xf
	v_add_f32_dpp v121, v121, v121 quad_perm:[1,0,3,2] row_mask:0xf bank_mask:0xf
	v_add_f32_dpp v118, v118, v118 quad_perm:[2,3,0,1] row_mask:0xf bank_mask:0xf
	v_add_f32_dpp v119, v119, v119 quad_perm:[2,3,0,1] row_mask:0xf bank_mask:0xf
	v_add_f32_dpp v120, v120, v120 quad_perm:[2,3,0,1] row_mask:0xf bank_mask:0xf
	v_add_f32_dpp v121, v121, v121 quad_perm:[2,3,0,1] row_mask:0xf bank_mask:0xf
	v_add_f32_dpp v118, v118, v118 row_half_mirror row_mask:0xf bank_mask:0xf
	v_add_f32_dpp v119, v119, v119 row_half_mirror row_mask:0xf bank_mask:0xf
	v_add_f32_dpp v120, v120, v120 row_half_mirror row_mask:0xf bank_mask:0xf
	v_add_f32_dpp v121, v121, v121 row_half_mirror row_mask:0xf bank_mask:0xf
	s_waitcnt vmcnt(18)
	v_cvt_pk_f32_fp8_e32 v[204:205], v180
	v_cvt_pk_f32_fp8_e32 v[206:207], v184
	v_pk_mul_f32 v[220:221], v[204:205], v[78:79]
	v_pk_mul_f32 v[222:223], v[206:207], v[78:79]
	v_cvt_pk_f32_fp8_sdwa v[208:209], v180 src0_sel:WORD_1
	v_cvt_pk_f32_fp8_sdwa v[210:211], v184 src0_sel:WORD_1
	v_pk_fma_f32 v[220:221], v[208:209], v[80:81], v[220:221]
	v_pk_fma_f32 v[222:223], v[210:211], v[80:81], v[222:223]
	v_cvt_pk_f32_fp8_e32 v[212:213], v181
	v_cvt_pk_f32_fp8_e32 v[214:215], v185
	v_pk_fma_f32 v[220:221], v[212:213], v[82:83], v[220:221]
	v_pk_fma_f32 v[222:223], v[214:215], v[82:83], v[222:223]
	v_cvt_pk_f32_fp8_sdwa v[216:217], v181 src0_sel:WORD_1
	v_cvt_pk_f32_fp8_sdwa v[218:219], v185 src0_sel:WORD_1
	v_pk_fma_f32 v[220:221], v[216:217], v[84:85], v[220:221]
	v_pk_fma_f32 v[222:223], v[218:219], v[84:85], v[222:223]
	v_cvt_pk_f32_fp8_e32 v[204:205], v182
	v_cvt_pk_f32_fp8_e32 v[206:207], v186
	v_pk_fma_f32 v[220:221], v[204:205], v[86:87], v[220:221]
	v_pk_fma_f32 v[222:223], v[206:207], v[86:87], v[222:223]
	v_cvt_pk_f32_fp8_sdwa v[208:209], v182 src0_sel:WORD_1
	v_cvt_pk_f32_fp8_sdwa v[210:211], v186 src0_sel:WORD_1
	v_pk_fma_f32 v[220:221], v[208:209], v[88:89], v[220:221]
	v_pk_fma_f32 v[222:223], v[210:211], v[88:89], v[222:223]
	v_cvt_pk_f32_fp8_e32 v[212:213], v183
	v_cvt_pk_f32_fp8_e32 v[214:215], v187
	v_pk_fma_f32 v[220:221], v[212:213], v[90:91], v[220:221]
	v_pk_fma_f32 v[222:223], v[214:215], v[90:91], v[222:223]
	v_cvt_pk_f32_fp8_sdwa v[216:217], v183 src0_sel:WORD_1
	v_cvt_pk_f32_fp8_sdwa v[218:219], v187 src0_sel:WORD_1
	v_pk_fma_f32 v[220:221], v[216:217], v[92:93], v[220:221]
	v_pk_fma_f32 v[222:223], v[218:219], v[92:93], v[222:223]
	s_waitcnt vmcnt(16)
; __device__ __forceinline__ void attn_phase(const Args& a, unsigned char* lds, int lane, int wave) {
;     ...
;             for (int i = 0; i < 8; ++i) { float kf[16]; unpack16_fp8(kk[i], kf); float d0 = 0.f, d1 = 0.f;
; #pragma unroll
;                 for (int x = 0; x < 16; x += 2) { d0 += q[x] * kf[x]; d1 += q[x + 1] * kf[x + 1]; }
;                 float d = d0 + d1;
;                 d += __shfl_xor(d, 1); d += __shfl_xor(d, 2); d += __shfl_xor(d, 4); s[i] = d; }
;             const float mn = fmaxf(fmaxf(fmaxf(mx, fmaxf(s[0], s[1])), fmaxf(s[2], s[3])), fmaxf(fmaxf(s[4], s[5]), fmaxf(s[6], s[7])));
;             const float al = __builtin_amdgcn_exp2f(mx - mn);
;             float p[8];
; #pragma unroll
;             for (int i = 0; i < 8; ++i) p[i] = __builtin_amdgcn_exp2f(s[i] - mn);
;             l = l * al + ((p[0] + p[1]) + (p[2] + p[3])) + ((p[4] + p[5]) + (p[6] + p[7]));
; #pragma unroll
;             for (int d = 0; d < 16; ++d) o[d] *= al;
; #pragma unroll
;             for (int i = 0; i < 8; ++i) { float vf[16]; unpack16_fp8(vv[i], vf);
; #pragma unroll
;                 for (int d = 0; d < 16; ++d) o[d] += p[i] * vf[d]; }
	v_cvt_pk_f32_fp8_e32 v[204:205], v188
	v_cvt_pk_f32_fp8_e32 v[206:207], v192
	v_pk_mul_f32 v[224:225], v[204:205], v[78:79]
	v_pk_mul_f32 v[226:227], v[206:207], v[78:79]
	v_cvt_pk_f32_fp8_sdwa v[208:209], v188 src0_sel:WORD_1
	v_cvt_pk_f32_fp8_sdwa v[210:211], v192 src0_sel:WORD_1
	v_pk_fma_f32 v[224:225], v[208:209], v[80:81], v[224:225]
	v_pk_fma_f32 v[226:227], v[210:211], v[80:81], v[226:227]
	v_cvt_pk_f32_fp8_e32 v[212:213], v189
	v_cvt_pk_f32_fp8_e32 v[214:215], v193
	v_pk_fma_f32 v[224:225], v[212:213], v[82:83], v[224:225]
	v_pk_fma_f32 v[226:227], v[214:215], v[82:83], v[226:227]
	v_cvt_pk_f32_fp8_sdwa v[216:217], v189 src0_sel:WORD_1
	v_cvt_pk_f32_fp8_sdwa v[218:219], v193 src0_sel:WORD_1
	v_pk_fma_f32 v[224:225], v[216:217], v[84:85], v[224:225]
	v_pk_fma_f32 v[226:227], v[218:219], v[84:85], v[226:227]
	v_cvt_pk_f32_fp8_e32 v[204:205], v190
	v_cvt_pk_f32_fp8_e32 v[206:207], v194
	v_pk_fma_f32 v[224:225], v[204:205], v[86:87], v[224:225]
	v_pk_fma_f32 v[226:227], v[206:207], v[86:87], v[226:227]
	v_cvt_pk_f32_fp8_sdwa v[208:209], v190 src0_sel:WORD_1
	v_cvt_pk_f32_fp8_sdwa v[210:211], v194 src0_sel:WORD_1
	v_pk_fma_f32 v[224:225], v[208:209], v[88:89], v[224:225]
	v_pk_fma_f32 v[226:227], v[210:211], v[88:89], v[226:227]
	v_cvt_pk_f32_fp8_e32 v[212:213], v191
	v_cvt_pk_f32_fp8_e32 v[214:215], v195
	v_pk_fma_f32 v[224:225], v[212:213], v[90:91], v[224:225]
	v_pk_fma_f32 v[226:227], v[214:215], v[90:91], v[226:227]
	v_cvt_pk_f32_fp8_sdwa v[216:217], v191 src0_sel:WORD_1
	v_cvt_pk_f32_fp8_sdwa v[218:219], v195 src0_sel:WORD_1
	v_pk_fma_f32 v[224:225], v[216:217], v[92:93], v[224:225]
	v_pk_fma_f32 v[226:227], v[218:219], v[92:93], v[226:227]
	v_add_f32_e32 v122, v220, v221
	v_add_f32_e32 v123, v222, v223
	v_add_f32_e32 v124, v224, v225
	v_add_f32_e32 v125, v226, v227
	v_add_f32_dpp v122, v122, v122 quad_perm:[1,0,3,2] row_mask:0xf bank_mask:0xf
	v_add_f32_dpp v123, v123, v123 quad_perm:[1,0,3,2] row_mask:0xf bank_mask:0xf
	v_add_f32_dpp v124, v124, v124 quad_perm:[1,0,3,2] row_mask:0xf bank_mask:0xf
	v_add_f32_dpp v125, v125, v125 quad_perm:[1,0,3,2] row_mask:0xf bank_mask:0xf
	v_add_f32_dpp v122, v122, v122 quad_perm:[2,3,0,1] row_mask:0xf bank_mask:0xf
	v_add_f32_dpp v123, v123, v123 quad_perm:[2,3,0,1] row_mask:0xf bank_mask:0xf
	v_add_f32_dpp v124, v124, v124 quad_perm:[2,3,0,1] row_mask:0xf bank_mask:0xf
	v_add_f32_dpp v125, v125, v125 quad_perm:[2,3,0,1] row_mask:0xf bank_mask:0xf
	v_add_f32_dpp v122, v122, v122 row_half_mirror row_mask:0xf bank_mask:0xf
	v_add_f32_dpp v123, v123, v123 row_half_mirror row_mask:0xf bank_mask:0xf
	v_add_f32_dpp v124, v124, v124 row_half_mirror row_mask:0xf bank_mask:0xf
	v_add_f32_dpp v125, v125, v125 row_half_mirror row_mask:0xf bank_mask:0xf
	v_max3_f32 v228, v110, v111, v112
	v_max3_f32 v229, v113, v114, v115
	v_max3_f32 v230, v116, v117, v118
	v_max3_f32 v231, v119, v120, v121
	v_max3_f32 v232, v122, v123, v124
	v_max3_f32 v233, v125, v109, v228
	v_max3_f32 v234, v229, v230, v231
	v_max3_f32 v235, v232, v233, v234
	v_sub_f32_e32 v236, v109, v235
	v_sub_f32_e32 v110, v110, v235
	v_sub_f32_e32 v111, v111, v235
	v_sub_f32_e32 v112, v112, v235
	v_sub_f32_e32 v113, v113, v235
	v_sub_f32_e32 v114, v114, v235
	v_sub_f32_e32 v115, v115, v235
	v_sub_f32_e32 v116, v116, v235
	v_sub_f32_e32 v117, v117, v235
	v_sub_f32_e32 v118, v118, v235
	v_sub_f32_e32 v119, v119, v235
	v_sub_f32_e32 v120, v120, v235
	v_sub_f32_e32 v121, v121, v235
	v_sub_f32_e32 v122, v122, v235
	v_sub_f32_e32 v123, v123, v235
	v_sub_f32_e32 v124, v124, v235
	v_sub_f32_e32 v125, v125, v235
	v_exp_f32_e32 v244, v236
	v_exp_f32_e32 v110, v110
	v_exp_f32_e32 v111, v111
	v_exp_f32_e32 v112, v112
	v_exp_f32_e32 v113, v113
	v_exp_f32_e32 v114, v114
	v_exp_f32_e32 v115, v115
	v_exp_f32_e32 v116, v116
	v_exp_f32_e32 v117, v117
	v_exp_f32_e32 v118, v118
	v_exp_f32_e32 v119, v119
	v_exp_f32_e32 v120, v120
	v_exp_f32_e32 v121, v121
	v_exp_f32_e32 v122, v122
	v_exp_f32_e32 v123, v123
	v_exp_f32_e32 v124, v124
	v_exp_f32_e32 v125, v125
	v_mov_b32_e32 v109, v235
	v_pk_mul_f32 v[62:63], v[62:63], v[244:245] op_sel_hi:[1,0]
	v_pk_mul_f32 v[64:65], v[64:65], v[244:245] op_sel_hi:[1,0]
	v_pk_mul_f32 v[66:67], v[66:67], v[244:245] op_sel_hi:[1,0]
	v_pk_mul_f32 v[68:69], v[68:69], v[244:245] op_sel_hi:[1,0]
	v_pk_mul_f32 v[70:71], v[70:71], v[244:245] op_sel_hi:[1,0]
	v_pk_mul_f32 v[72:73], v[72:73], v[244:245] op_sel_hi:[1,0]
	v_pk_mul_f32 v[74:75], v[74:75], v[244:245] op_sel_hi:[1,0]
	v_pk_mul_f32 v[76:77], v[76:77], v[244:245] op_sel_hi:[1,0]
	v_add_f32_e32 v228, v110, v111
	v_add_f32_e32 v229, v112, v113
	v_add_f32_e32 v230, v114, v115
	v_add_f32_e32 v231, v116, v117
	v_add_f32_e32 v232, v118, v119
	v_add_f32_e32 v233, v120, v121
	v_add_f32_e32 v234, v122, v123
	v_add_f32_e32 v235, v124, v125
	v_add_f32_e32 v228, v228, v229
	v_add_f32_e32 v230, v230, v231
	v_add_f32_e32 v232, v232, v233
	v_add_f32_e32 v234, v234, v235
	v_add_f32_e32 v228, v228, v230
	v_add_f32_e32 v232, v232, v234
	v_add_f32_e32 v228, v228, v232
	v_fma_f32 v108, v108, v244, v228
	s_waitcnt vmcnt(15)
	v_cvt_pk_f32_fp8_e32 v[204:205], v0
	v_cvt_pk_f32_fp8_sdwa v[206:207], v0 src0_sel:WORD_1
	v_pk_fma_f32 v[62:63], v[204:205], v[110:111], v[62:63] op_sel_hi:[1,0,1]
	v_pk_fma_f32 v[64:65], v[206:207], v[110:111], v[64:65] op_sel_hi:[1,0,1]
	v_cvt_pk_f32_fp8_e32 v[208:209], v1
	v_cvt_pk_f32_fp8_sdwa v[210:211], v1 src0_sel:WORD_1
	v_pk_fma_f32 v[66:67], v[208:209], v[110:111], v[66:67] op_sel_hi:[1,0,1]
	v_pk_fma_f32 v[68:69], v[210:211], v[110:111], v[68:69] op_sel_hi:[1,0,1]
	v_cvt_pk_f32_fp8_e32 v[212:213], v2
	v_cvt_pk_f32_fp8_sdwa v[214:215], v2 src0_sel:WORD_1
	v_pk_fma_f32 v[70:71], v[212:213], v[110:111], v[70:71] op_sel_hi:[1,0,1]
	v_pk_fma_f32 v[72:73], v[214:215], v[110:111], v[72:73] op_sel_hi:[1,0,1]
	v_cvt_pk_f32_fp8_e32 v[216:217], v3
	v_cvt_pk_f32_fp8_sdwa v[218:219], v3 src0_sel:WORD_1
	v_pk_fma_f32 v[74:75], v[216:217], v[110:111], v[74:75] op_sel_hi:[1,0,1]
	v_pk_fma_f32 v[76:77], v[218:219], v[110:111], v[76:77] op_sel_hi:[1,0,1]
	s_waitcnt vmcnt(14)
; __device__ __forceinline__ void attn_phase(const Args& a, unsigned char* lds, int lane, int wave) {
;     ...
;             for (int i = 0; i < 8; ++i) { float vf[16]; unpack16_fp8(vv[i], vf);
; #pragma unroll
;                 for (int d = 0; d < 16; ++d) o[d] += p[i] * vf[d]; }
	v_cvt_pk_f32_fp8_e32 v[204:205], v4
	v_cvt_pk_f32_fp8_sdwa v[206:207], v4 src0_sel:WORD_1
	v_pk_fma_f32 v[62:63], v[204:205], v[110:111], v[62:63] op_sel:[0,1,0] op_sel_hi:[1,1,1]
	v_pk_fma_f32 v[64:65], v[206:207], v[110:111], v[64:65] op_sel:[0,1,0] op_sel_hi:[1,1,1]
	v_cvt_pk_f32_fp8_e32 v[208:209], v5
	v_cvt_pk_f32_fp8_sdwa v[210:211], v5 src0_sel:WORD_1
	v_pk_fma_f32 v[66:67], v[208:209], v[110:111], v[66:67] op_sel:[0,1,0] op_sel_hi:[1,1,1]
	v_pk_fma_f32 v[68:69], v[210:211], v[110:111], v[68:69] op_sel:[0,1,0] op_sel_hi:[1,1,1]
	v_cvt_pk_f32_fp8_e32 v[212:213], v6
	v_cvt_pk_f32_fp8_sdwa v[214:215], v6 src0_sel:WORD_1
	v_pk_fma_f32 v[70:71], v[212:213], v[110:111], v[70:71] op_sel:[0,1,0] op_sel_hi:[1,1,1]
	v_pk_fma_f32 v[72:73], v[214:215], v[110:111], v[72:73] op_sel:[0,1,0] op_sel_hi:[1,1,1]
	v_cvt_pk_f32_fp8_e32 v[216:217], v7
	v_cvt_pk_f32_fp8_sdwa v[218:219], v7 src0_sel:WORD_1
	v_pk_fma_f32 v[74:75], v[216:217], v[110:111], v[74:75] op_sel:[0,1,0] op_sel_hi:[1,1,1]
	v_pk_fma_f32 v[76:77], v[218:219], v[110:111], v[76:77] op_sel:[0,1,0] op_sel_hi:[1,1,1]
	s_waitcnt vmcnt(13)
	v_cvt_pk_f32_fp8_e32 v[204:205], v8
	v_cvt_pk_f32_fp8_sdwa v[206:207], v8 src0_sel:WORD_1
	v_pk_fma_f32 v[62:63], v[204:205], v[112:113], v[62:63] op_sel_hi:[1,0,1]
	v_pk_fma_f32 v[64:65], v[206:207], v[112:113], v[64:65] op_sel_hi:[1,0,1]
	v_cvt_pk_f32_fp8_e32 v[208:209], v9
	v_cvt_pk_f32_fp8_sdwa v[210:211], v9 src0_sel:WORD_1
	v_pk_fma_f32 v[66:67], v[208:209], v[112:113], v[66:67] op_sel_hi:[1,0,1]
	v_pk_fma_f32 v[68:69], v[210:211], v[112:113], v[68:69] op_sel_hi:[1,0,1]
	v_cvt_pk_f32_fp8_e32 v[212:213], v10
	v_cvt_pk_f32_fp8_sdwa v[214:215], v10 src0_sel:WORD_1
	v_pk_fma_f32 v[70:71], v[212:213], v[112:113], v[70:71] op_sel_hi:[1,0,1]
	v_pk_fma_f32 v[72:73], v[214:215], v[112:113], v[72:73] op_sel_hi:[1,0,1]
	v_cvt_pk_f32_fp8_e32 v[216:217], v11
	v_cvt_pk_f32_fp8_sdwa v[218:219], v11 src0_sel:WORD_1
	v_pk_fma_f32 v[74:75], v[216:217], v[112:113], v[74:75] op_sel_hi:[1,0,1]
	v_pk_fma_f32 v[76:77], v[218:219], v[112:113], v[76:77] op_sel_hi:[1,0,1]
	s_waitcnt vmcnt(12)
	v_cvt_pk_f32_fp8_e32 v[204:205], v12
	v_cvt_pk_f32_fp8_sdwa v[206:207], v12 src0_sel:WORD_1
	v_pk_fma_f32 v[62:63], v[204:205], v[112:113], v[62:63] op_sel:[0,1,0] op_sel_hi:[1,1,1]
	v_pk_fma_f32 v[64:65], v[206:207], v[112:113], v[64:65] op_sel:[0,1,0] op_sel_hi:[1,1,1]
	v_cvt_pk_f32_fp8_e32 v[208:209], v13
	v_cvt_pk_f32_fp8_sdwa v[210:211], v13 src0_sel:WORD_1
	v_pk_fma_f32 v[66:67], v[208:209], v[112:113], v[66:67] op_sel:[0,1,0] op_sel_hi:[1,1,1]
	v_pk_fma_f32 v[68:69], v[210:211], v[112:113], v[68:69] op_sel:[0,1,0] op_sel_hi:[1,1,1]
	v_cvt_pk_f32_fp8_e32 v[212:213], v14
	v_cvt_pk_f32_fp8_sdwa v[214:215], v14 src0_sel:WORD_1
	v_pk_fma_f32 v[70:71], v[212:213], v[112:113], v[70:71] op_sel:[0,1,0] op_sel_hi:[1,1,1]
	v_pk_fma_f32 v[72:73], v[214:215], v[112:113], v[72:73] op_sel:[0,1,0] op_sel_hi:[1,1,1]
	v_cvt_pk_f32_fp8_e32 v[216:217], v15
	v_cvt_pk_f32_fp8_sdwa v[218:219], v15 src0_sel:WORD_1
	v_pk_fma_f32 v[74:75], v[216:217], v[112:113], v[74:75] op_sel:[0,1,0] op_sel_hi:[1,1,1]
	v_pk_fma_f32 v[76:77], v[218:219], v[112:113], v[76:77] op_sel:[0,1,0] op_sel_hi:[1,1,1]
	s_waitcnt vmcnt(11)
	v_cvt_pk_f32_fp8_e32 v[204:205], v16
	v_cvt_pk_f32_fp8_sdwa v[206:207], v16 src0_sel:WORD_1
	v_pk_fma_f32 v[62:63], v[204:205], v[114:115], v[62:63] op_sel_hi:[1,0,1]
	v_pk_fma_f32 v[64:65], v[206:207], v[114:115], v[64:65] op_sel_hi:[1,0,1]
	v_cvt_pk_f32_fp8_e32 v[208:209], v17
	v_cvt_pk_f32_fp8_sdwa v[210:211], v17 src0_sel:WORD_1
	v_pk_fma_f32 v[66:67], v[208:209], v[114:115], v[66:67] op_sel_hi:[1,0,1]
	v_pk_fma_f32 v[68:69], v[210:211], v[114:115], v[68:69] op_sel_hi:[1,0,1]
	v_cvt_pk_f32_fp8_e32 v[212:213], v18
	v_cvt_pk_f32_fp8_sdwa v[214:215], v18 src0_sel:WORD_1
	v_pk_fma_f32 v[70:71], v[212:213], v[114:115], v[70:71] op_sel_hi:[1,0,1]
	v_pk_fma_f32 v[72:73], v[214:215], v[114:115], v[72:73] op_sel_hi:[1,0,1]
	v_cvt_pk_f32_fp8_e32 v[216:217], v19
	v_cvt_pk_f32_fp8_sdwa v[218:219], v19 src0_sel:WORD_1
	v_pk_fma_f32 v[74:75], v[216:217], v[114:115], v[74:75] op_sel_hi:[1,0,1]
	v_pk_fma_f32 v[76:77], v[218:219], v[114:115], v[76:77] op_sel_hi:[1,0,1]
	s_waitcnt vmcnt(10)
	v_cvt_pk_f32_fp8_e32 v[204:205], v20
	v_cvt_pk_f32_fp8_sdwa v[206:207], v20 src0_sel:WORD_1
	v_pk_fma_f32 v[62:63], v[204:205], v[114:115], v[62:63] op_sel:[0,1,0] op_sel_hi:[1,1,1]
	v_pk_fma_f32 v[64:65], v[206:207], v[114:115], v[64:65] op_sel:[0,1,0] op_sel_hi:[1,1,1]
	v_cvt_pk_f32_fp8_e32 v[208:209], v21
	v_cvt_pk_f32_fp8_sdwa v[210:211], v21 src0_sel:WORD_1
	v_pk_fma_f32 v[66:67], v[208:209], v[114:115], v[66:67] op_sel:[0,1,0] op_sel_hi:[1,1,1]
	v_pk_fma_f32 v[68:69], v[210:211], v[114:115], v[68:69] op_sel:[0,1,0] op_sel_hi:[1,1,1]
	v_cvt_pk_f32_fp8_e32 v[212:213], v22
	v_cvt_pk_f32_fp8_sdwa v[214:215], v22 src0_sel:WORD_1
	v_pk_fma_f32 v[70:71], v[212:213], v[114:115], v[70:71] op_sel:[0,1,0] op_sel_hi:[1,1,1]
	v_pk_fma_f32 v[72:73], v[214:215], v[114:115], v[72:73] op_sel:[0,1,0] op_sel_hi:[1,1,1]
	v_cvt_pk_f32_fp8_e32 v[216:217], v23
	v_cvt_pk_f32_fp8_sdwa v[218:219], v23 src0_sel:WORD_1
	v_pk_fma_f32 v[74:75], v[216:217], v[114:115], v[74:75] op_sel:[0,1,0] op_sel_hi:[1,1,1]
	v_pk_fma_f32 v[76:77], v[218:219], v[114:115], v[76:77] op_sel:[0,1,0] op_sel_hi:[1,1,1]
	s_waitcnt vmcnt(9)
; __device__ __forceinline__ void attn_phase(const Args& a, unsigned char* lds, int lane, int wave) {
;     ...
;             for (int i = 0; i < 8; ++i) { float vf[16]; unpack16_fp8(vv[i], vf);
; #pragma unroll
;                 for (int d = 0; d < 16; ++d) o[d] += p[i] * vf[d]; }
	v_cvt_pk_f32_fp8_e32 v[204:205], v24
	v_cvt_pk_f32_fp8_sdwa v[206:207], v24 src0_sel:WORD_1
	v_pk_fma_f32 v[62:63], v[204:205], v[116:117], v[62:63] op_sel_hi:[1,0,1]
	v_pk_fma_f32 v[64:65], v[206:207], v[116:117], v[64:65] op_sel_hi:[1,0,1]
	v_cvt_pk_f32_fp8_e32 v[208:209], v25
	v_cvt_pk_f32_fp8_sdwa v[210:211], v25 src0_sel:WORD_1
	v_pk_fma_f32 v[66:67], v[208:209], v[116:117], v[66:67] op_sel_hi:[1,0,1]
	v_pk_fma_f32 v[68:69], v[210:211], v[116:117], v[68:69] op_sel_hi:[1,0,1]
	v_cvt_pk_f32_fp8_e32 v[212:213], v26
	v_cvt_pk_f32_fp8_sdwa v[214:215], v26 src0_sel:WORD_1
	v_pk_fma_f32 v[70:71], v[212:213], v[116:117], v[70:71] op_sel_hi:[1,0,1]
	v_pk_fma_f32 v[72:73], v[214:215], v[116:117], v[72:73] op_sel_hi:[1,0,1]
	v_cvt_pk_f32_fp8_e32 v[216:217], v27
	v_cvt_pk_f32_fp8_sdwa v[218:219], v27 src0_sel:WORD_1
	v_pk_fma_f32 v[74:75], v[216:217], v[116:117], v[74:75] op_sel_hi:[1,0,1]
	v_pk_fma_f32 v[76:77], v[218:219], v[116:117], v[76:77] op_sel_hi:[1,0,1]
	s_waitcnt vmcnt(8)
	v_cvt_pk_f32_fp8_e32 v[204:205], v28
	v_cvt_pk_f32_fp8_sdwa v[206:207], v28 src0_sel:WORD_1
	v_pk_fma_f32 v[62:63], v[204:205], v[116:117], v[62:63] op_sel:[0,1,0] op_sel_hi:[1,1,1]
	v_pk_fma_f32 v[64:65], v[206:207], v[116:117], v[64:65] op_sel:[0,1,0] op_sel_hi:[1,1,1]
	v_cvt_pk_f32_fp8_e32 v[208:209], v29
	v_cvt_pk_f32_fp8_sdwa v[210:211], v29 src0_sel:WORD_1
	v_pk_fma_f32 v[66:67], v[208:209], v[116:117], v[66:67] op_sel:[0,1,0] op_sel_hi:[1,1,1]
	v_pk_fma_f32 v[68:69], v[210:211], v[116:117], v[68:69] op_sel:[0,1,0] op_sel_hi:[1,1,1]
	v_cvt_pk_f32_fp8_e32 v[212:213], v30
	v_cvt_pk_f32_fp8_sdwa v[214:215], v30 src0_sel:WORD_1
	v_pk_fma_f32 v[70:71], v[212:213], v[116:117], v[70:71] op_sel:[0,1,0] op_sel_hi:[1,1,1]
	v_pk_fma_f32 v[72:73], v[214:215], v[116:117], v[72:73] op_sel:[0,1,0] op_sel_hi:[1,1,1]
	v_cvt_pk_f32_fp8_e32 v[216:217], v31
	v_cvt_pk_f32_fp8_sdwa v[218:219], v31 src0_sel:WORD_1
	v_pk_fma_f32 v[74:75], v[216:217], v[116:117], v[74:75] op_sel:[0,1,0] op_sel_hi:[1,1,1]
	v_pk_fma_f32 v[76:77], v[218:219], v[116:117], v[76:77] op_sel:[0,1,0] op_sel_hi:[1,1,1]
	s_waitcnt vmcnt(7)
	v_cvt_pk_f32_fp8_e32 v[204:205], v32
	v_cvt_pk_f32_fp8_sdwa v[206:207], v32 src0_sel:WORD_1
	v_pk_fma_f32 v[62:63], v[204:205], v[118:119], v[62:63] op_sel_hi:[1,0,1]
	v_pk_fma_f32 v[64:65], v[206:207], v[118:119], v[64:65] op_sel_hi:[1,0,1]
	v_cvt_pk_f32_fp8_e32 v[208:209], v33
	v_cvt_pk_f32_fp8_sdwa v[210:211], v33 src0_sel:WORD_1
	v_pk_fma_f32 v[66:67], v[208:209], v[118:119], v[66:67] op_sel_hi:[1,0,1]
	v_pk_fma_f32 v[68:69], v[210:211], v[118:119], v[68:69] op_sel_hi:[1,0,1]
	v_cvt_pk_f32_fp8_e32 v[212:213], v34
	v_cvt_pk_f32_fp8_sdwa v[214:215], v34 src0_sel:WORD_1
	v_pk_fma_f32 v[70:71], v[212:213], v[118:119], v[70:71] op_sel_hi:[1,0,1]
	v_pk_fma_f32 v[72:73], v[214:215], v[118:119], v[72:73] op_sel_hi:[1,0,1]
	v_cvt_pk_f32_fp8_e32 v[216:217], v35
	v_cvt_pk_f32_fp8_sdwa v[218:219], v35 src0_sel:WORD_1
	v_pk_fma_f32 v[74:75], v[216:217], v[118:119], v[74:75] op_sel_hi:[1,0,1]
	v_pk_fma_f32 v[76:77], v[218:219], v[118:119], v[76:77] op_sel_hi:[1,0,1]
	s_waitcnt vmcnt(6)
	v_cvt_pk_f32_fp8_e32 v[204:205], v36
	v_cvt_pk_f32_fp8_sdwa v[206:207], v36 src0_sel:WORD_1
	v_pk_fma_f32 v[62:63], v[204:205], v[118:119], v[62:63] op_sel:[0,1,0] op_sel_hi:[1,1,1]
	v_pk_fma_f32 v[64:65], v[206:207], v[118:119], v[64:65] op_sel:[0,1,0] op_sel_hi:[1,1,1]
	v_cvt_pk_f32_fp8_e32 v[208:209], v37
	v_cvt_pk_f32_fp8_sdwa v[210:211], v37 src0_sel:WORD_1
	v_pk_fma_f32 v[66:67], v[208:209], v[118:119], v[66:67] op_sel:[0,1,0] op_sel_hi:[1,1,1]
	v_pk_fma_f32 v[68:69], v[210:211], v[118:119], v[68:69] op_sel:[0,1,0] op_sel_hi:[1,1,1]
	v_cvt_pk_f32_fp8_e32 v[212:213], v38
	v_cvt_pk_f32_fp8_sdwa v[214:215], v38 src0_sel:WORD_1
	v_pk_fma_f32 v[70:71], v[212:213], v[118:119], v[70:71] op_sel:[0,1,0] op_sel_hi:[1,1,1]
	v_pk_fma_f32 v[72:73], v[214:215], v[118:119], v[72:73] op_sel:[0,1,0] op_sel_hi:[1,1,1]
	v_cvt_pk_f32_fp8_e32 v[216:217], v39
	v_cvt_pk_f32_fp8_sdwa v[218:219], v39 src0_sel:WORD_1
	v_pk_fma_f32 v[74:75], v[216:217], v[118:119], v[74:75] op_sel:[0,1,0] op_sel_hi:[1,1,1]
	v_pk_fma_f32 v[76:77], v[218:219], v[118:119], v[76:77] op_sel:[0,1,0] op_sel_hi:[1,1,1]
	s_waitcnt vmcnt(5)
	v_cvt_pk_f32_fp8_e32 v[204:205], v40
	v_cvt_pk_f32_fp8_sdwa v[206:207], v40 src0_sel:WORD_1
	v_pk_fma_f32 v[62:63], v[204:205], v[120:121], v[62:63] op_sel_hi:[1,0,1]
	v_pk_fma_f32 v[64:65], v[206:207], v[120:121], v[64:65] op_sel_hi:[1,0,1]
	v_cvt_pk_f32_fp8_e32 v[208:209], v41
	v_cvt_pk_f32_fp8_sdwa v[210:211], v41 src0_sel:WORD_1
	v_pk_fma_f32 v[66:67], v[208:209], v[120:121], v[66:67] op_sel_hi:[1,0,1]
	v_pk_fma_f32 v[68:69], v[210:211], v[120:121], v[68:69] op_sel_hi:[1,0,1]
	v_cvt_pk_f32_fp8_e32 v[212:213], v42
	v_cvt_pk_f32_fp8_sdwa v[214:215], v42 src0_sel:WORD_1
	v_pk_fma_f32 v[70:71], v[212:213], v[120:121], v[70:71] op_sel_hi:[1,0,1]
	v_pk_fma_f32 v[72:73], v[214:215], v[120:121], v[72:73] op_sel_hi:[1,0,1]
	v_cvt_pk_f32_fp8_e32 v[216:217], v43
	v_cvt_pk_f32_fp8_sdwa v[218:219], v43 src0_sel:WORD_1
	v_pk_fma_f32 v[74:75], v[216:217], v[120:121], v[74:75] op_sel_hi:[1,0,1]
	v_pk_fma_f32 v[76:77], v[218:219], v[120:121], v[76:77] op_sel_hi:[1,0,1]
	s_waitcnt vmcnt(4)
; __device__ __forceinline__ u32x4 pack8(const float* v) { u32x4 w; w.x = pk2(v[0], v[1]); w.y = pk2(v[2], v[3]); w.z = pk2(v[4], v[5]); w.w = pk2(v[6], v[7]); return w; }
; __device__ __forceinline__ void attn_phase(const Args& a, unsigned char* lds, int lane, int wave) {
;     ...
;     for (int t = gw; t < TT; t += NGW) {
;         const bool sample = t >= TP; const int bb = sample ? (t - TP) >> 6 : 0;
;         const int c = t >> 6; const int L = sample ? 1088 : 64 * (c + 1);
;     ...
;             for (int i = 0; i < 8; ++i) { float vf[16]; unpack16_fp8(vv[i], vf);
; #pragma unroll
;                 for (int d = 0; d < 16; ++d) o[d] += p[i] * vf[d]; }
;             mx = mn;
;         }
;         const float il = 1.f / l;
; #pragma unroll
;         for (int d = 0; d < 16; ++d) o[d] *= il;
;         *(u32x4*)qp = pack8(o); *(u32x4*)(qp + 8) = pack8(o + 8);
	v_cvt_pk_f32_fp8_e32 v[204:205], v44
	v_cvt_pk_f32_fp8_sdwa v[206:207], v44 src0_sel:WORD_1
	v_pk_fma_f32 v[62:63], v[204:205], v[120:121], v[62:63] op_sel:[0,1,0] op_sel_hi:[1,1,1]
	v_pk_fma_f32 v[64:65], v[206:207], v[120:121], v[64:65] op_sel:[0,1,0] op_sel_hi:[1,1,1]
	v_cvt_pk_f32_fp8_e32 v[208:209], v45
	v_cvt_pk_f32_fp8_sdwa v[210:211], v45 src0_sel:WORD_1
	v_pk_fma_f32 v[66:67], v[208:209], v[120:121], v[66:67] op_sel:[0,1,0] op_sel_hi:[1,1,1]
	v_pk_fma_f32 v[68:69], v[210:211], v[120:121], v[68:69] op_sel:[0,1,0] op_sel_hi:[1,1,1]
	v_cvt_pk_f32_fp8_e32 v[212:213], v46
	v_cvt_pk_f32_fp8_sdwa v[214:215], v46 src0_sel:WORD_1
	v_pk_fma_f32 v[70:71], v[212:213], v[120:121], v[70:71] op_sel:[0,1,0] op_sel_hi:[1,1,1]
	v_pk_fma_f32 v[72:73], v[214:215], v[120:121], v[72:73] op_sel:[0,1,0] op_sel_hi:[1,1,1]
	v_cvt_pk_f32_fp8_e32 v[216:217], v47
	v_cvt_pk_f32_fp8_sdwa v[218:219], v47 src0_sel:WORD_1
	v_pk_fma_f32 v[74:75], v[216:217], v[120:121], v[74:75] op_sel:[0,1,0] op_sel_hi:[1,1,1]
	v_pk_fma_f32 v[76:77], v[218:219], v[120:121], v[76:77] op_sel:[0,1,0] op_sel_hi:[1,1,1]
	s_waitcnt vmcnt(3)
	v_cvt_pk_f32_fp8_e32 v[204:205], v48
	v_cvt_pk_f32_fp8_sdwa v[206:207], v48 src0_sel:WORD_1
	v_pk_fma_f32 v[62:63], v[204:205], v[122:123], v[62:63] op_sel_hi:[1,0,1]
	v_pk_fma_f32 v[64:65], v[206:207], v[122:123], v[64:65] op_sel_hi:[1,0,1]
	v_cvt_pk_f32_fp8_e32 v[208:209], v49
	v_cvt_pk_f32_fp8_sdwa v[210:211], v49 src0_sel:WORD_1
	v_pk_fma_f32 v[66:67], v[208:209], v[122:123], v[66:67] op_sel_hi:[1,0,1]
	v_pk_fma_f32 v[68:69], v[210:211], v[122:123], v[68:69] op_sel_hi:[1,0,1]
	v_cvt_pk_f32_fp8_e32 v[212:213], v50
	v_cvt_pk_f32_fp8_sdwa v[214:215], v50 src0_sel:WORD_1
	v_pk_fma_f32 v[70:71], v[212:213], v[122:123], v[70:71] op_sel_hi:[1,0,1]
	v_pk_fma_f32 v[72:73], v[214:215], v[122:123], v[72:73] op_sel_hi:[1,0,1]
	v_cvt_pk_f32_fp8_e32 v[216:217], v51
	v_cvt_pk_f32_fp8_sdwa v[218:219], v51 src0_sel:WORD_1
	v_pk_fma_f32 v[74:75], v[216:217], v[122:123], v[74:75] op_sel_hi:[1,0,1]
	v_pk_fma_f32 v[76:77], v[218:219], v[122:123], v[76:77] op_sel_hi:[1,0,1]
	s_waitcnt vmcnt(2)
	v_cvt_pk_f32_fp8_e32 v[204:205], v52
	v_cvt_pk_f32_fp8_sdwa v[206:207], v52 src0_sel:WORD_1
	v_pk_fma_f32 v[62:63], v[204:205], v[122:123], v[62:63] op_sel:[0,1,0] op_sel_hi:[1,1,1]
	v_pk_fma_f32 v[64:65], v[206:207], v[122:123], v[64:65] op_sel:[0,1,0] op_sel_hi:[1,1,1]
	v_cvt_pk_f32_fp8_e32 v[208:209], v53
	v_cvt_pk_f32_fp8_sdwa v[210:211], v53 src0_sel:WORD_1
	v_pk_fma_f32 v[66:67], v[208:209], v[122:123], v[66:67] op_sel:[0,1,0] op_sel_hi:[1,1,1]
	v_pk_fma_f32 v[68:69], v[210:211], v[122:123], v[68:69] op_sel:[0,1,0] op_sel_hi:[1,1,1]
	v_cvt_pk_f32_fp8_e32 v[212:213], v54
	v_cvt_pk_f32_fp8_sdwa v[214:215], v54 src0_sel:WORD_1
	v_pk_fma_f32 v[70:71], v[212:213], v[122:123], v[70:71] op_sel:[0,1,0] op_sel_hi:[1,1,1]
	v_pk_fma_f32 v[72:73], v[214:215], v[122:123], v[72:73] op_sel:[0,1,0] op_sel_hi:[1,1,1]
	v_cvt_pk_f32_fp8_e32 v[216:217], v55
	v_cvt_pk_f32_fp8_sdwa v[218:219], v55 src0_sel:WORD_1
	v_pk_fma_f32 v[74:75], v[216:217], v[122:123], v[74:75] op_sel:[0,1,0] op_sel_hi:[1,1,1]
	v_pk_fma_f32 v[76:77], v[218:219], v[122:123], v[76:77] op_sel:[0,1,0] op_sel_hi:[1,1,1]
	s_waitcnt vmcnt(1)
	v_cvt_pk_f32_fp8_e32 v[204:205], v196
	v_cvt_pk_f32_fp8_sdwa v[206:207], v196 src0_sel:WORD_1
	v_pk_fma_f32 v[62:63], v[204:205], v[124:125], v[62:63] op_sel_hi:[1,0,1]
	v_pk_fma_f32 v[64:65], v[206:207], v[124:125], v[64:65] op_sel_hi:[1,0,1]
	v_cvt_pk_f32_fp8_e32 v[208:209], v197
	v_cvt_pk_f32_fp8_sdwa v[210:211], v197 src0_sel:WORD_1
	v_pk_fma_f32 v[66:67], v[208:209], v[124:125], v[66:67] op_sel_hi:[1,0,1]
	v_pk_fma_f32 v[68:69], v[210:211], v[124:125], v[68:69] op_sel_hi:[1,0,1]
	v_cvt_pk_f32_fp8_e32 v[212:213], v198
	v_cvt_pk_f32_fp8_sdwa v[214:215], v198 src0_sel:WORD_1
	v_pk_fma_f32 v[70:71], v[212:213], v[124:125], v[70:71] op_sel_hi:[1,0,1]
	v_pk_fma_f32 v[72:73], v[214:215], v[124:125], v[72:73] op_sel_hi:[1,0,1]
	v_cvt_pk_f32_fp8_e32 v[216:217], v199
	v_cvt_pk_f32_fp8_sdwa v[218:219], v199 src0_sel:WORD_1
	v_pk_fma_f32 v[74:75], v[216:217], v[124:125], v[74:75] op_sel_hi:[1,0,1]
	v_pk_fma_f32 v[76:77], v[218:219], v[124:125], v[76:77] op_sel_hi:[1,0,1]
	s_waitcnt vmcnt(0)
	v_cvt_pk_f32_fp8_e32 v[204:205], v200
	v_cvt_pk_f32_fp8_sdwa v[206:207], v200 src0_sel:WORD_1
	v_pk_fma_f32 v[62:63], v[204:205], v[124:125], v[62:63] op_sel:[0,1,0] op_sel_hi:[1,1,1]
	v_pk_fma_f32 v[64:65], v[206:207], v[124:125], v[64:65] op_sel:[0,1,0] op_sel_hi:[1,1,1]
	v_cvt_pk_f32_fp8_e32 v[208:209], v201
	v_cvt_pk_f32_fp8_sdwa v[210:211], v201 src0_sel:WORD_1
	v_pk_fma_f32 v[66:67], v[208:209], v[124:125], v[66:67] op_sel:[0,1,0] op_sel_hi:[1,1,1]
	v_pk_fma_f32 v[68:69], v[210:211], v[124:125], v[68:69] op_sel:[0,1,0] op_sel_hi:[1,1,1]
	v_cvt_pk_f32_fp8_e32 v[212:213], v202
	v_cvt_pk_f32_fp8_sdwa v[214:215], v202 src0_sel:WORD_1
	v_pk_fma_f32 v[70:71], v[212:213], v[124:125], v[70:71] op_sel:[0,1,0] op_sel_hi:[1,1,1]
	v_pk_fma_f32 v[72:73], v[214:215], v[124:125], v[72:73] op_sel:[0,1,0] op_sel_hi:[1,1,1]
	v_cvt_pk_f32_fp8_e32 v[216:217], v203
	v_cvt_pk_f32_fp8_sdwa v[218:219], v203 src0_sel:WORD_1
	v_pk_fma_f32 v[74:75], v[216:217], v[124:125], v[74:75] op_sel:[0,1,0] op_sel_hi:[1,1,1]
	v_pk_fma_f32 v[76:77], v[218:219], v[124:125], v[76:77] op_sel:[0,1,0] op_sel_hi:[1,1,1]
	v_div_scale_f32 v0, s[0:1], v108, v108, 1.0
	v_rcp_f32_e32 v1, v0
	v_div_scale_f32 v2, vcc, 1.0, v108, 1.0
	s_add_i32 s2, s2, s28
	v_fma_f32 v3, -v0, v1, 1.0
	v_fmac_f32_e32 v1, v3, v1
	v_mul_f32_e32 v3, v2, v1
	v_fma_f32 v4, -v0, v3, v2
	v_fmac_f32_e32 v3, v4, v1
	v_fma_f32 v0, -v0, v3, v2
	v_div_fmas_f32 v0, v0, v1, v3
	v_div_fixup_f32 v0, v0, v108, 1.0
	v_pk_mul_f32 v[62:63], v[62:63], v[0:1] op_sel_hi:[1,0]
	v_pk_mul_f32 v[64:65], v[64:65], v[0:1] op_sel_hi:[1,0]
	v_pk_mul_f32 v[66:67], v[66:67], v[0:1] op_sel_hi:[1,0]
	v_pk_mul_f32 v[68:69], v[68:69], v[0:1] op_sel_hi:[1,0]
	v_pk_mul_f32 v[70:71], v[70:71], v[0:1] op_sel_hi:[1,0]
	v_pk_mul_f32 v[72:73], v[72:73], v[0:1] op_sel_hi:[1,0]
	v_pk_mul_f32 v[74:75], v[74:75], v[0:1] op_sel_hi:[1,0]
	v_pk_mul_f32 v[76:77], v[76:77], v[0:1] op_sel_hi:[1,0]
	v_cvt_pk_bf16_f32 v4, v62, v63
	v_cvt_pk_bf16_f32 v5, v64, v65
	v_cvt_pk_bf16_f32 v6, v66, v67
	v_cvt_pk_bf16_f32 v7, v68, v69
	v_cvt_pk_bf16_f32 v8, v70, v71
	v_cvt_pk_bf16_f32 v9, v72, v73
	v_cvt_pk_bf16_f32 v10, v74, v75
	v_cvt_pk_bf16_f32 v11, v76, v77
	global_store_dwordx4 v[60:61], v[4:7], off
	global_store_dwordx4 v[60:61], v[8:11], off offset:16
	s_cmpk_lg_i32 s66, 0x100
	s_cbranch_scc1 .Lat_generic_next
	s_cmpk_lt_i32 s2, 0x4000
	s_cbranch_scc1 .Lat_q
	s_sub_i32 s0, s2, s28
	s_cmpk_gt_i32 s0, 0x3fff
	s_cbranch_scc1 .Lat_done
	s_cmp_gt_u32 s96, 1
	s_cbranch_scc1 .Lat_done
	s_and_b32 s0, s74, 7
	s_lshl_b32 s0, s0, 6
	s_lshr_b32 s1, s74, 3
	s_lshl_b32 s1, s1, 1
	s_add_i32 s2, s0, s1
	s_add_i32 s2, s2, s96
	s_addk_i32 s2, 0x4000
	s_branch .Lat_q
; __device__ __forceinline__ void gla_g3(const Args& a, unsigned char* lds, int tid, int lane, int wave) {
;     bf16_t* P = (bf16_t*)(a.ws + WS_P);
;     const float* bc = (const float*)(lds + L_BC);
;     bf16_t* Q = (bf16_t*)(lds + L_A);
;     bf16_t* Kk = (bf16_t*)(lds + L_A + 17408);
;     bf16_t* VT = (bf16_t*)(lds + L_A + 34816);
;     bf16_t* ATS = (bf16_t*)(lds + L_A + 71680);
;     float* RS = (float*)(lds + L_A + 80896);
;     bf16_t* OUTS = (bf16_t*)(lds + L_A);
;     const int l15 = lane & 15, q = lane >> 4;
;     for (int it = gridDim.x - 1 - blockIdx.x; it < NCH * 4; it += gridDim.x) {
;         const int n = it >> 2, h = it & 3;
;         { const f32x4* bcg = (const f32x4*)(a.ws + WS_BC) + (size_t)it * 2048; f32x4* bcl = (f32x4*)(lds + L_BC);
; #pragma unroll
;           for (int i = 0; i < 4; ++i) bcl[tid + 512 * i] = bcg[tid + 512 * i]; }
;         __syncthreads();
;         for (int ch = tid; ch < 1024; ch += 512) { const int s = ch >> 4, d0 = (ch & 15) * 8; float v[8], o[8];
;             unpack8(*(const u32x4*)(P + (size_t)(n * 64 + s) * NP + C_GQ + h * 128 + d0), v);
; #pragma unroll
;             for (int i = 0; i < 8; ++i) o[i] = v[i] * 0.08838834764831845f * __expf(bc[s * 128 + d0 + i]);
;             *(u32x4*)(Q + s * 136 + d0) = pack8(o);
;             unpack8(*(const u32x4*)(P + (size_t)(n * 64 + s) * NP + C_GK + h * 128 + d0), v);
; #pragma unroll
;             for (int i = 0; i < 8; ++i) o[i] = v[i] * __expf(-bc[s * 128 + d0 + i]);
;             *(u32x4*)(Kk + s * 136 + d0) = pack8(o); }
;         for (int ch = tid; ch < 2048; ch += 512) { const int s = ch >> 5, d0 = (ch & 31) * 8; const u32x4 w = *(const u32x4*)(P + (size_t)(n * 64 + s) * NP + C_GV + h * 256 + d0);
;             VT[(d0 + 0) * 72 + (s ^ tsw(d0))] = (bf16_t)(w.x & 0xffff); VT[(d0 + 1) * 72 + (s ^ tsw(d0))] = (bf16_t)(w.x >> 16); VT[(d0 + 2) * 72 + (s ^ tsw(d0))] = (bf16_t)(w.y & 0xffff); VT[(d0 + 3) * 72 + (s ^ tsw(d0))] = (bf16_t)(w.y >> 16);
;             VT[(d0 + 4) * 72 + (s ^ tsw(d0))] = (bf16_t)(w.z & 0xffff); VT[(d0 + 5) * 72 + (s ^ tsw(d0))] = (bf16_t)(w.z >> 16); VT[(d0 + 6) * 72 + (s ^ tsw(d0))] = (bf16_t)(w.w & 0xffff); VT[(d0 + 7) * 72 + (s ^ tsw(d0))] = (bf16_t)(w.w >> 16); }
;         __syncthreads();
; #pragma unroll
;         for (int ti = 0; ti < 2; ++ti) { const int id = wave * 2 + ti, mt = id >> 2, nt = id & 3;
.Lat_generic_next:
	s_cmpk_gt_i32 s2, 0x41ff
	s_cbranch_scc0 .Lat_q
.Lat_done:
.LBB0_1925:
	s_not_b32 s0, s74
	s_add_i32 s2, s66, s0
	s_cmpk_gt_i32 s2, 0x41f
	s_waitcnt vmcnt(0) lgkmcnt(0)
	s_barrier
	s_cbranch_scc1 .LBB0_1934
	s_add_u32 s10, s62, 0xad00000
	s_addc_u32 s11, s63, 0
	s_lshl_b32 s0, s96, 3
	v_and_b32_e32 v2, 15, v128
	v_lshrrev_b32_e32 v3, 4, v130
	s_and_b32 s4, s0, 0x1ffffff0
	v_and_b32_e32 v4, 48, v130
	v_or_b32_e32 v5, s4, v2
	v_lshlrev_b32_e32 v7, 3, v3
	v_add_u32_e32 v6, 0, v4
	s_movk_i32 s5, 0x110
	v_mad_u64_u32 v[36:37], s[0:1], v5, s5, v[6:7]
	s_lshl_b32 s0, s96, 4
	v_lshlrev_b32_e32 v3, 2, v3
	s_and_b32 s0, s0, 48
	s_lshl_b32 s3, s96, 5
	v_or_b32_e32 v5, s4, v3
	s_lshr_b32 s22, s97, 8
	v_or_b32_e32 v37, s0, v3
	v_or_b32_e32 v3, s0, v2
	v_mad_u32_u24 v68, v3, s5, v6
	v_mul_u32_u24_e32 v3, 0x90, v3
	s_add_i32 s16, 0, 0x1b000
	s_lshl_b32 s4, s22, 2
	v_and_or_b32 v12, s3, 32, v2
	v_or_b32_e32 v13, 1, v5
	v_or_b32_e32 v14, 2, v5
	v_or_b32_e32 v15, 3, v5
	s_movk_i32 s24, 0x90
	v_add3_u32 v69, s16, v3, v4
	v_mbcnt_lo_u32_b32 v3, -1, 0
	s_add_i32 s25, s4, 0
	v_mul_u32_u24_e32 v27, 0x110, v12
	v_lshl_add_u32 v28, v12, 1, s16
	v_cmp_gt_u32_e64 s[4:5], v12, v5
	v_cmp_gt_u32_e64 s[6:7], v12, v13
	v_cmp_gt_u32_e64 s[8:9], v12, v14
	v_cmp_gt_u32_e64 s[12:13], v12, v15
	v_or_b32_e32 v12, 16, v12
	s_lshl_b32 s26, s22, 7
	v_mbcnt_hi_u32_b32 v3, -1, v3
	v_mul_lo_u32 v29, v5, s24
	v_cmp_gt_u32_e64 s[14:15], v12, v5
	v_lshlrev_b32_e32 v5, 1, v12
	v_or_b32_e32 v38, s26, v2
	v_and_b32_e32 v9, 64, v3
	v_add3_u32 v77, s16, v29, v5
	v_lshlrev_b32_e32 v5, 7, v2
	v_xor_b32_e32 v8, 1, v3
	v_add_u32_e32 v9, 64, v9
	v_lshl_or_b32 v40, s22, 14, v5
	v_mul_lo_u32 v5, v38, s24
	s_add_i32 s39, 0, 0x12000
	v_cmp_lt_i32_e32 vcc, v8, v9
	v_add_u32_e32 v5, s39, v5
	v_bitop3_b32 v31, v7, v128, 8 bitop3:0x78
	v_or_b32_e32 v32, 16, v2
	v_cndmask_b32_e32 v8, v3, v8, vcc
	v_lshlrev_b32_e32 v31, 1, v31
	v_bitop3_b32 v34, v32, v7, 24 bitop3:0x6c
	v_or_b32_e32 v35, 32, v2
	v_add_u32_e32 v47, 0x2400, v5
	v_lshlrev_b32_e32 v70, 2, v8
	v_xor_b32_e32 v8, 2, v3
	v_add_u32_e32 v81, v5, v31
	v_add_u32_e32 v33, 0x900, v5
	v_lshlrev_b32_e32 v34, 1, v34
	v_bitop3_b32 v43, v35, v7, 40 bitop3:0x6c
	v_or_b32_e32 v44, 48, v2
	v_add_u32_e32 v85, v47, v31
	v_add_u32_e32 v31, 0x2d00, v5
	v_cmp_lt_i32_e32 vcc, v8, v9
	v_add_u32_e32 v82, v33, v34
	v_add_u32_e32 v42, 0x1200, v5
	v_lshlrev_b32_e32 v43, 1, v43
	v_bitop3_b32 v46, v44, v7, 56 bitop3:0x6c
	v_add_u32_e32 v86, v31, v34
	v_add_u32_e32 v34, 0x3600, v5
	v_cndmask_b32_e32 v8, v3, v8, vcc
	v_and_b32_e32 v30, 8, v128
	v_add_u32_e32 v83, v42, v43
	v_add_u32_e32 v45, 0x1b00, v5
	v_lshlrev_b32_e32 v46, 1, v46
	v_add_u32_e32 v87, v34, v43
	v_add_u32_e32 v43, 0x3f00, v5
	v_lshlrev_b32_e32 v71, 2, v8
	v_xor_b32_e32 v8, 4, v3
	v_add_u32_e32 v84, v45, v46
	v_add_u32_e32 v88, v43, v46
	v_or_b32_e32 v46, 32, v7
	v_bitop3_b32 v7, v7, v30, 32 bitop3:0x36
	v_cmp_lt_i32_e32 vcc, v8, v9
	v_lshlrev_b32_e32 v7, 1, v7
	v_add_u32_e32 v89, v5, v7
	v_cndmask_b32_e32 v8, v3, v8, vcc
	v_bitop3_b32 v5, v32, v46, 24 bitop3:0x6c
	v_bitop3_b32 v32, v44, v46, 56 bitop3:0x6c
	v_mov_b32_e32 v0, s80
	v_mov_b32_e32 v1, s81
	v_mov_b32_e32 v39, 0
	v_lshlrev_b32_e32 v72, 2, v8
	v_xor_b32_e32 v8, 8, v3
	v_lshlrev_b32_e32 v32, 1, v32
	v_add_u32_e32 v93, v47, v7
	v_or_b32_e32 v7, 1, v37
	v_cmp_lt_i32_e32 vcc, v8, v9
	v_lshlrev_b32_e32 v74, 3, v128
	v_add_u32_e32 v11, 0x200, v128
	v_or_b32_e32 v10, 0x400, v128
	v_add_u32_e32 v26, 0x600, v128
	v_lshlrev_b32_e32 v5, 1, v5
	v_bitop3_b32 v30, v35, v46, 40 bitop3:0x6c
	v_add_u32_e32 v92, v45, v32
	v_add_u32_e32 v96, v43, v32
	v_lshlrev_b32_e32 v32, 1, v38
	v_lshl_add_u64 v[44:45], v[38:39], 2, v[0:1]
	v_mul_u32_u24_e32 v0, 0x210, v7
	v_lshrrev_b32_e32 v107, 4, v128
	v_cndmask_b32_e32 v3, v3, v8, vcc
	s_add_i32 s25, s25, 0x1d400
	v_and_b32_e32 v8, 0xf8, v74
	v_lshrrev_b32_e32 v75, 5, v128
	v_cmp_gt_u32_e64 s[16:17], v12, v13
	v_cmp_gt_u32_e64 s[18:19], v12, v14
	v_cmp_gt_u32_e64 s[20:21], v12, v15
	v_or_b32_e32 v12, 0x800, v40
	v_or_b32_e32 v14, 0x1000, v40
	v_or_b32_e32 v16, 0x1800, v40
	v_or_b32_e32 v18, 0x2000, v40
	v_or_b32_e32 v20, 0x2800, v40
	v_or_b32_e32 v22, 0x3000, v40
	v_or_b32_e32 v24, 0x3800, v40
	v_add_u32_e32 v90, v33, v5
	v_lshlrev_b32_e32 v30, 1, v30
	v_add_u32_e32 v94, v31, v5
	v_lshlrev_b32_e32 v97, 3, v37
	v_mul_u32_u24_e32 v5, 0x210, v37
	v_lshrrev_b32_e32 v100, 5, v11
	v_lshrrev_b32_e32 v101, 5, v10
	v_lshrrev_b32_e32 v102, 5, v26
	v_add3_u32 v103, 0, v0, v32
	v_mul_u32_u24_e32 v0, 0x110, v107
	v_lshlrev_b32_e32 v1, 4, v2
	v_lshlrev_b32_e32 v73, 2, v3
	v_lshl_add_u32 v3, v8, 1, 0
	v_mul_u32_u24_e32 v9, 0x210, v75
	v_ashrrev_i32_e32 v13, 31, v12
	v_ashrrev_i32_e32 v15, 31, v14
	v_ashrrev_i32_e32 v17, 31, v16
	v_ashrrev_i32_e32 v19, 31, v18
	v_ashrrev_i32_e32 v21, 31, v20
	v_ashrrev_i32_e32 v23, 31, v22
	v_ashrrev_i32_e32 v25, 31, v24
	v_add_u32_e32 v91, v42, v30
	v_add_u32_e32 v95, v34, v30
	v_lshlrev_b32_e32 v30, 3, v7
	v_or_b32_e32 v31, 24, v97
	v_add3_u32 v99, 0, v5, v32
	v_mul_u32_u24_e32 v11, 0x210, v100
	v_mul_u32_u24_e32 v33, 0x210, v101
	v_mul_u32_u24_e32 v26, 0x210, v102
	s_add_u32 s42, s62, 0x2900000
	v_mov_b32_e32 v5, v39
	v_add3_u32 v0, v0, v1, 0
	s_mov_b32 s23, 0
	v_cmp_eq_u32_e64 s[0:1], 0, v2
	v_lshl_add_u32 v76, v128, 4, 0
	v_add_u32_e32 v78, 0x90, v77
	v_add_u32_e32 v79, 0x120, v77
	v_add_u32_e32 v80, 0x1b0, v77
	v_ashrrev_i32_e32 v41, 31, v40
	s_movk_i32 s33, 0x2000
	s_movk_i32 s37, 0x3000
	v_or_b32_e32 v98, 16, v97
	s_addc_u32 s43, s63, 0
	v_lshl_add_u64 v[42:43], s[60:61], 0, v[4:5]
	v_add_u32_e32 v104, 0x210, v103
	v_add_u32_e32 v105, 0x420, v103
	v_add_u32_e32 v106, 0xfffffe00, v128
	v_add_u32_e32 v108, 0x9800, v0
	v_lshl_add_u32 v109, v107, 9, 0
	v_lshlrev_b32_e32 v110, 5, v2
	s_lshl_b32 s48, s2, 4
	s_lshl_b32 s49, s66, 4
	v_lshlrev_b32_e32 v46, 4, v128
	v_lshlrev_b32_e32 v111, 4, v10
	s_movk_i32 s50, 0x3a00
	s_mov_b32 s24, 0x3db504f3
	s_movk_i32 s51, 0x5ff
	v_add_u32_e32 v112, v6, v27
	s_movk_i32 s52, 0x7fff
	v_add_u32_e32 v113, v28, v29
	v_lshlrev_b32_e32 v48, 1, v2
	s_lshl_b32 s26, s26, 1
	s_mov_b64 s[28:29], 0x3000
	v_lshlrev_b64 v[50:51], 1, v[12:13]
	v_lshlrev_b64 v[52:53], 1, v[14:15]
	v_lshlrev_b64 v[54:55], 1, v[16:17]
	v_lshlrev_b64 v[56:57], 1, v[18:19]
	v_lshlrev_b64 v[58:59], 1, v[20:21]
	v_lshlrev_b64 v[60:61], 1, v[22:23]
	v_lshlrev_b64 v[62:63], 1, v[24:25]
	s_mov_b64 s[30:31], 0x80
	s_mov_b64 s[34:35], 0xc0
	v_add_u32_e32 v114, s25, v30
	v_add_u32_e32 v115, s25, v31
	s_mov_b32 s36, 0x3b800000
	s_mov_b32 s38, 0x358637bd
	s_mov_b32 s53, 0x800000
	v_add_u32_e32 v116, v3, v9
	v_lshlrev_b32_e32 v64, 1, v8
	v_add_u32_e32 v117, v3, v11
	v_add_u32_e32 v118, v3, v33
	v_add_u32_e32 v119, v3, v26
	s_branch .LBB0_1928
